# phase 0 reorder (half WGs convert weights before adaLN GEMV); hand-written QK-norm/RoPE with LDS sincos table; phase 4 reorder + GLA/attention LDS pipelining
# baseline (speedup 1.0000x reference)
; #define LAS __attribute__((address_space(3)))
; __device__ __forceinline__ float silu_f(float x) { return x / (1.f + __expf(-x)); }
; #define RUN_PH(ph) if ((ph) == ONLY_PH && P.ph_lo <= (ph) && (ph) < P.ph_hi)
; #define RUN_PH(ph) if (P.ph_lo <= (ph) && (ph) < P.ph_hi)
; __device__ __forceinline__ void ada_phase(const Params& P, LAS unsigned char* lds) {
;     const int tid = threadIdx.x;
;     LAS f32x4* sA = (LAS f32x4*)lds;
;     LAS f32x4* sB = sA + 2048;
;     LAS float* sC = (LAS float*)(sB + 2048);
;     LAS float* part = sC + 2048;
;     const float* c = P.in[1]; const float* cc = P.in[3];
;     for (int i = tid; i < 2048; i += 512) {
;         sA[i] = (f32x4){silu_f(c[0 * 2048 + i]), silu_f(c[1 * 2048 + i]), silu_f(c[2 * 2048 + i]), silu_f(c[3 * 2048 + i])};
;         sB[i] = (f32x4){silu_f(c[4 * 2048 + i]), silu_f(c[5 * 2048 + i]), silu_f(c[6 * 2048 + i]), silu_f(c[7 * 2048 + i])};
;         sC[i] = silu_f(cc[i]); }
; __global__ void __launch_bounds__(512, 2) mega(Params P) {
;     ...
;     RUN_PH(0) { ada_phase(P, lds); __syncthreads(); weights_phase(P, lds); }
.LBB0_17:
	s_add_u32 s84, s50, 0xb340000
	s_addc_u32 s85, s51, 0
	s_load_dwordx16 s[52:67], s[0:1], 0x0
	s_load_dwordx16 s[68:83], s[0:1], 0x40
	s_cmp_lt_i32 s24, 1
	s_cselect_b64 s[16:17], -1, 0
	s_cmp_gt_i32 s25, 0
	s_cselect_b64 s[0:1], -1, 0
	s_and_b64 s[0:1], s[16:17], s[0:1]
	v_writelane_b32 v242, s12, 3
	s_andn2_b64 vcc, exec, s[0:1]
	s_nop 0
	v_writelane_b32 v242, s13, 4
	s_cbranch_vccnz .LBB0_122
	s_mov_b32 s99, 0
	s_bitcmp1_b32 s22, 3
	s_cbranch_scc0 .Lp0_ada
	s_mov_b32 s99, 1
	s_waitcnt lgkmcnt(0)
	s_branch .LBB0_30
.Lp0_ada:
	v_lshlrev_b32_e32 v0, 2, v224
	v_add_u32_e32 v1, 0, v0
	v_add_u32_e32 v2, 0xfffffe00, v224
	v_add_u32_e32 v3, 0x10000, v1
	v_lshl_add_u32 v4, v224, 4, 0
	v_mov_b32_e32 v1, 0
	s_mov_b64 s[18:19], 0
	s_mov_b32 s20, 0x8000
	s_mov_b32 s21, 0xa000
	s_mov_b32 s28, 0xc000
	s_mov_b32 s29, 0xe000
	s_movk_i32 s30, 0x5ff

; #define LAS __attribute__((address_space(3)))
; __device__ __forceinline__ void weights_phase(const Params& P, LAS unsigned char* lds) {
;     const int tid = threadIdx.x, lane = tid & 63, wave = __builtin_amdgcn_readfirstlane(tid >> 6);
;     LAS float* scr = (LAS float*)(lds + wave * 8704);
;     const int gw = blockIdx.x * 8 + wave, NGW = gridDim.x * 8;
;     constexpr int I_IN = (D / 64) * (INC / 32), I_SQ = (D / 64) * (D / 32), I_1 = (D / 64) * (DFF / 32), I_2 = (DFF / 64) * (D / 32);
;     constexpr int NIT = I_IN + 2 * I_SQ + 2 * I_1 + 2 * I_2;
;     bf16_t* ws16;
;     for (int it = gw; it < NIT; it += NGW) {
;         int r = it;
;         if (r < I_IN) { ws16 = (bf16_t*)(P.ws + WS_WIN); transpose_item(P.in[10], D, INC, ws16, scr, r, lane); continue; } r -= I_IN;
.LBB0_30:
	s_cmp_eq_u32 s99, 2
	s_cbranch_scc1 .LBB0_122
	v_readfirstlane_b32 s0, v224
	s_lshr_b32 s0, s0, 6
	s_lshl_b32 s1, s22, 3
	s_add_i32 s6, s0, s1
	s_mov_b64 s[8:9], s[96:97]
	s_cmp_gt_i32 s6, 0xa21f
	s_barrier
	s_cbranch_scc1 .LBB0_49
	s_mulk_i32 s0, 0x2200
	v_bfe_u32 v10, v224, 5, 1
	v_and_b32_e32 v8, 31, v224
	s_add_i32 s0, s0, 0
	v_lshlrev_b32_e32 v0, 2, v8
	v_mul_u32_u24_e32 v2, 0x84, v10
	v_add3_u32 v11, s0, v0, v2
	v_lshlrev_b32_e32 v0, 3, v224
	s_lshl_b32 s7, s26, 3
	v_bfe_u32 v12, v224, 3, 3
	v_and_b32_e32 v24, 56, v0
	v_mul_u32_u24_e32 v0, 0x84, v24
	v_lshlrev_b32_e32 v2, 2, v12
	s_add_u32 s31, s50, 0x6300000
	v_mov_b32_e32 v1, 0
	v_add3_u32 v13, s0, v0, v2
	v_lshlrev_b32_e32 v0, 1, v24
	s_addc_u32 s0, s51, 0
	v_lshl_add_u64 v[2:3], s[50:51], 0, v[0:1]
	v_writelane_b32 v242, s0, 5
	s_mov_b64 s[0:1], 0x1b00000
	s_add_u32 s10, s50, 0x2300000
	v_lshl_add_u64 v[4:5], v[2:3], 0, s[0:1]
	s_mov_b64 s[0:1], 0x1300000
	v_or_b32_e32 v14, 8, v12
	v_or_b32_e32 v15, 16, v12
	v_or_b32_e32 v16, 24, v12
	s_addc_u32 s11, s51, 0
	v_lshl_add_u64 v[6:7], v[2:3], 0, s[0:1]
	s_lshl_b32 s12, s6, 5
	s_lshl_b32 s13, s26, 8
	s_movk_i32 s14, 0x4000
	s_mov_b32 s15, 0x8000
	s_mov_b32 s18, 0xc000
	s_mov_b32 s19, 0x10000
	s_mov_b32 s28, 0x14000
	s_mov_b32 s29, 0x18000
	s_mov_b32 s33, 0x1c000
	s_mov_b32 s34, 0x20000
	s_mov_b32 s35, 0x24000
	s_mov_b32 s54, 0x28000
	s_mov_b32 s55, 0x2c000
	s_mov_b32 s58, 0x30000
	s_mov_b32 s59, 0x34000
	s_mov_b32 s60, 0x38000
	s_mov_b32 s61, 0x3c000
	s_mov_b32 s62, 0x40000
	s_mov_b32 s63, 0x44000
	s_mov_b32 s86, 0x48000
	s_mov_b32 s87, 0x4c000
	s_mov_b32 s88, 0x50000
	s_mov_b32 s89, 0x54000
	s_mov_b32 s90, 0x58000
	s_mov_b32 s91, 0x5c000
	s_mov_b32 s92, 0x60000
	s_mov_b32 s93, 0x64000
	s_mov_b32 s94, 0x68000
	s_mov_b32 s95, 0x6c000
	s_mov_b32 s96, 0x70000
	s_mov_b32 s97, 0x74000
	s_mov_b32 s20, 0x78000
	s_mov_b32 s21, 0x7c000
	s_mov_b32 s30, 0xd0000
	v_lshlrev_b32_e32 v0, 2, v8
	v_add_u32_e32 v17, 0x400, v11
	v_add_u32_e32 v18, 0x800, v11
	v_add_u32_e32 v19, 0xc00, v11
	v_add_u32_e32 v20, 0x1000, v11
	v_add_u32_e32 v21, 0x1400, v11
	v_add_u32_e32 v22, 0x1800, v11
	v_add_u32_e32 v23, 0x1c00, v11
	v_lshlrev_b32_e32 v8, 1, v24
	s_mov_b32 s1, 0
	s_branch .LBB0_33

; __device__ __forceinline__ unsigned cvt_pk_bf16(float lo, float hi) { const f32x2 v = {lo, hi}; const bf16v2_t b = __builtin_convertvector(v, bf16v2_t); return __builtin_bit_cast(unsigned, b); }
; #define RUN_PH(ph) if ((ph) == ONLY_PH && P.ph_lo <= (ph) && (ph) < P.ph_hi)
; #define RUN_PH(ph) if (P.ph_lo <= (ph) && (ph) < P.ph_hi)
; __device__ __forceinline__ void weights_phase(const Params& P, LAS unsigned char* lds) {
;     ...
;     const int gt = blockIdx.x * 512 + tid, NGT = gridDim.x * 512;
;     bf16_t* CN = (bf16_t*)(P.ws + WS_CN);
;     for (int idx = gt; idx < 2048 * 256; idx += NGT) { const int k = idx >> 8, j0 = (idx & 255) * 8; float v[8];
; #pragma unroll
;         for (int e = 0; e < 8; ++e) { const int j = j0 + e; const int t = j & 1023; const float a = (float)((k * t) & 2047) * (1.f / 1024.f);
;             v[e] = (j < 1024) ? cospif(a) : (t == 0 ? ((k & 1) ? -1.f : 1.f) : -sinpif(a)); }
;         u32x4 o; o.x = cvt_pk_bf16(v[0], v[1]); o.y = cvt_pk_bf16(v[2], v[3]); o.z = cvt_pk_bf16(v[4], v[5]); o.w = cvt_pk_bf16(v[6], v[7]);
;         *(u32x4*)(CN + (size_t)k * 2048 + j0) = o; }
;     bf16_t* CMA = (bf16_t*)(P.ws + WS_CMA);
;     for (int idx = gt; idx < 512 * 32; idx += NGT) { const int r = idx >> 5, c0 = (idx & 31) * 8; float v[8];
; #pragma unroll
;         for (int e = 0; e < 8; ++e) { const int cix = c0 + e; const float a = (float)(((r & 255) * cix) & 255) * (1.f / 128.f); v[e] = (r < 256) ? cospif(a) : sinpif(a); }
;         u32x4 o; o.x = cvt_pk_bf16(v[0], v[1]); o.y = cvt_pk_bf16(v[2], v[3]); o.z = cvt_pk_bf16(v[4], v[5]); o.w = cvt_pk_bf16(v[6], v[7]);
;         *(u32x4*)(CMA + (size_t)r * 256 + c0) = o; }
; }
; __global__ void __launch_bounds__(512, 2) mega(Params P) {
;     ...
;     RUN_PH(0) { ada_phase(P, lds); __syncthreads(); weights_phase(P, lds); }
.LBB0_121:
	s_or_b64 exec, exec, s[2:3]
	s_cmp_lg_u32 s99, 1
	s_cbranch_scc1 .LBB0_122
	s_mov_b32 s99, 2
	s_sub_u32 s4, s96, 0xc8
	s_subb_u32 s5, s97, 0
	s_load_dwordx16 s[52:67], s[4:5], 0x0
	s_waitcnt lgkmcnt(0)
	s_barrier
	s_branch .Lp0_ada

; __device__ __forceinline__ void prep_phase(const Params& P, LAS unsigned char* lds) {
;     ...
;     {
;         const int i = tid & 31; const float invf = powf(10000.f, -(float)i / 32.f);
;         const int NHR = NTOK * 10 + NCTX * 2;
;         const float gq0 = P.in[11][i], gq1 = P.in[11][32 + i], gq2 = P.in[11][64 + i], gq3 = P.in[11][96 + i];
;         const float gk0 = P.in[12][i], gk1 = P.in[12][32 + i], gk2 = P.in[12][64 + i], gk3 = P.in[12][96 + i];
;         const int hw = blockIdx.x * 16 + (tid >> 5), nhw = gridDim.x * 16;
;         for (int base = 0; base < NHR; base += 4 * nhw) {
;     ...
;                     float sr, cr, sc_, cc_; sincosf((float)rr * invf, &sr, &cr); sincosf((float)cc * invf, &sc_, &cc_);
.Lpa_begin:
	s_lshl_b32 s1, s26, 4
	s_lshl_b32 s99, s1, 2
	s_mov_b32 s98, 0xcccccccd
	s_mov_b32 s2, 0x3f22f983
	s_mov_b32 s3, 0xbfc90fda
	s_add_u32 s4, s50, 0x26718000
	s_addc_u32 s5, s51, 0
	s_mov_b32 s0, 0
	v_and_b32_e32 v131, 31, v224
	v_lshlrev_b32_e32 v128, 1, v131
	v_lshlrev_b32_e32 v130, 3, v131
	v_lshlrev_b32_e32 v143, 2, v131
	v_lshrrev_b32_e32 v144, 5, v224
	v_lshl_add_u32 v129, s22, 4, v144
	global_load_dword v132, v143, s[74:75] offset:0
	global_load_dword v133, v143, s[74:75] offset:128
	global_load_dword v134, v143, s[74:75] offset:256
	global_load_dword v135, v143, s[74:75] offset:384
	global_load_dword v136, v143, s[76:77] offset:0
	global_load_dword v137, v143, s[76:77] offset:128
	global_load_dword v138, v143, s[76:77] offset:256
	global_load_dword v139, v143, s[76:77] offset:384
	v_mov_b32_e32 v140, 0x358637bd
	v_mov_b32_e32 v141, 0x3c0881c4
	v_mov_b32_e32 v142, 0xbab64f3b
	v_add_u32_e32 v32, 0, v144
	v_lshl_add_u32 v43, v32, 8, v130
	v_cvt_f32_u32_e32 v32, v32
	v_mul_f32_e32 v32, v28, v32
	v_mul_f32_e64 v33, |v32|, s2
	v_rndne_f32_e32 v33, v33
	v_cvt_i32_f32_e32 v36, v33
	v_fma_f32 v37, v33, s3, |v32|
	v_fmac_f32_e32 v37, 0xb3a22168, v33
	v_fmac_f32_e32 v37, 0xa7c234c4, v33
	v_mul_f32_e32 v38, v37, v37
	v_fmamk_f32 v34, v38, 0xb94c1982, v141
	v_fmaak_f32 v34, v38, v34, 0xbe2aaa9d
	v_mul_f32_e32 v34, v38, v34
	v_fmamk_f32 v35, v38, 0x37d75334, v142
	v_fmaak_f32 v35, v38, v35, 0x3d2aabf7
	v_fmaak_f32 v35, v38, v35, 0xbf000004
	v_fmac_f32_e32 v37, v37, v34
	v_fma_f32 v35, v38, v35, 1.0
	v_lshlrev_b32_e32 v39, 30, v36
	v_and_b32_e32 v36, 1, v36
	v_and_b32_e32 v41, 0x7fffffff, v32
	v_xor_b32_e32 v41, v41, v32
	v_and_b32_e32 v40, 0x80000000, v39
	v_cmp_eq_u32_e32 vcc, 0, v36
	v_xor_b32_e32 v39, 0x80000000, v37
	s_nop 1
	v_cndmask_b32_e32 v42, v35, v37, vcc
	v_cndmask_b32_e32 v39, v39, v35, vcc
	v_xor_b32_e32 v41, v41, v42
	v_xor_b32_e32 v34, v41, v40
	v_xor_b32_e32 v35, v39, v40
	ds_write_b64 v43, v[34:35]
	v_add_u32_e32 v44, 16, v144
	v_lshl_add_u32 v55, v44, 8, v130
	v_cvt_f32_u32_e32 v44, v44
	v_mul_f32_e32 v44, v28, v44
	v_mul_f32_e64 v45, |v44|, s2
	v_rndne_f32_e32 v45, v45
	v_cvt_i32_f32_e32 v48, v45
	v_fma_f32 v49, v45, s3, |v44|
	v_fmac_f32_e32 v49, 0xb3a22168, v45
	v_fmac_f32_e32 v49, 0xa7c234c4, v45
	v_mul_f32_e32 v50, v49, v49
	v_fmamk_f32 v46, v50, 0xb94c1982, v141
	v_fmaak_f32 v46, v50, v46, 0xbe2aaa9d
	v_mul_f32_e32 v46, v50, v46
	v_fmamk_f32 v47, v50, 0x37d75334, v142
	v_fmaak_f32 v47, v50, v47, 0x3d2aabf7
	v_fmaak_f32 v47, v50, v47, 0xbf000004
	v_fmac_f32_e32 v49, v49, v46
	v_fma_f32 v47, v50, v47, 1.0
	v_lshlrev_b32_e32 v51, 30, v48
	v_and_b32_e32 v48, 1, v48
	v_and_b32_e32 v53, 0x7fffffff, v44
	v_xor_b32_e32 v53, v53, v44
	v_and_b32_e32 v52, 0x80000000, v51
	v_cmp_eq_u32_e32 vcc, 0, v48
	v_xor_b32_e32 v51, 0x80000000, v49
	s_nop 1
	v_cndmask_b32_e32 v54, v47, v49, vcc
	v_cndmask_b32_e32 v51, v51, v47, vcc
	v_xor_b32_e32 v53, v53, v54
	v_xor_b32_e32 v46, v53, v52
	v_xor_b32_e32 v47, v51, v52
	ds_write_b64 v55, v[46:47]
	v_add_u32_e32 v56, 32, v144
	v_lshl_add_u32 v67, v56, 8, v130
	v_cvt_f32_u32_e32 v56, v56
	v_mul_f32_e32 v56, v28, v56
	v_mul_f32_e64 v57, |v56|, s2
	v_rndne_f32_e32 v57, v57
	v_cvt_i32_f32_e32 v60, v57
	v_fma_f32 v61, v57, s3, |v56|
	v_fmac_f32_e32 v61, 0xb3a22168, v57
	v_fmac_f32_e32 v61, 0xa7c234c4, v57
	v_mul_f32_e32 v62, v61, v61
	v_fmamk_f32 v58, v62, 0xb94c1982, v141
	v_fmaak_f32 v58, v62, v58, 0xbe2aaa9d
	v_mul_f32_e32 v58, v62, v58
	v_fmamk_f32 v59, v62, 0x37d75334, v142
	v_fmaak_f32 v59, v62, v59, 0x3d2aabf7
	v_fmaak_f32 v59, v62, v59, 0xbf000004
	v_fmac_f32_e32 v61, v61, v58
	v_fma_f32 v59, v62, v59, 1.0
	v_lshlrev_b32_e32 v63, 30, v60
	v_and_b32_e32 v60, 1, v60
	v_and_b32_e32 v65, 0x7fffffff, v56
	v_xor_b32_e32 v65, v65, v56
	v_and_b32_e32 v64, 0x80000000, v63
	v_cmp_eq_u32_e32 vcc, 0, v60
	v_xor_b32_e32 v63, 0x80000000, v61
	s_nop 1
	v_cndmask_b32_e32 v66, v59, v61, vcc
	v_cndmask_b32_e32 v63, v63, v59, vcc
	v_xor_b32_e32 v65, v65, v66
	v_xor_b32_e32 v58, v65, v64
	v_xor_b32_e32 v59, v63, v64
	ds_write_b64 v67, v[58:59]
	v_add_u32_e32 v68, 48, v144
	v_lshl_add_u32 v79, v68, 8, v130
	v_cvt_f32_u32_e32 v68, v68
	v_mul_f32_e32 v68, v28, v68
	v_mul_f32_e64 v69, |v68|, s2
	v_rndne_f32_e32 v69, v69
	v_cvt_i32_f32_e32 v72, v69
	v_fma_f32 v73, v69, s3, |v68|
	v_fmac_f32_e32 v73, 0xb3a22168, v69
	v_fmac_f32_e32 v73, 0xa7c234c4, v69
	v_mul_f32_e32 v74, v73, v73
	v_fmamk_f32 v70, v74, 0xb94c1982, v141
	v_fmaak_f32 v70, v74, v70, 0xbe2aaa9d
	v_mul_f32_e32 v70, v74, v70
	v_fmamk_f32 v71, v74, 0x37d75334, v142
	v_fmaak_f32 v71, v74, v71, 0x3d2aabf7
	v_fmaak_f32 v71, v74, v71, 0xbf000004
	v_fmac_f32_e32 v73, v73, v70
	v_fma_f32 v71, v74, v71, 1.0
	v_lshlrev_b32_e32 v75, 30, v72
	v_and_b32_e32 v72, 1, v72
	v_and_b32_e32 v77, 0x7fffffff, v68
	v_xor_b32_e32 v77, v77, v68
	v_and_b32_e32 v76, 0x80000000, v75
	v_cmp_eq_u32_e32 vcc, 0, v72
	v_xor_b32_e32 v75, 0x80000000, v73
	s_nop 1
	v_cndmask_b32_e32 v78, v71, v73, vcc
	v_cndmask_b32_e32 v75, v75, v71, vcc
	v_xor_b32_e32 v77, v77, v78
	v_xor_b32_e32 v70, v77, v76
	v_xor_b32_e32 v71, v75, v76
	ds_write_b64 v79, v[70:71]
	s_waitcnt vmcnt(0) lgkmcnt(0)
	s_barrier
; __device__ __forceinline__ void prep_phase(const Params& P, LAS unsigned char* lds) {
;     ...
;         for (int base = 0; base < NHR; base += 4 * nhw) {
;             float xv[4][4]; int rows[4], hhs[4];
; #pragma unroll
;             for (int u = 0; u < 4; ++u) {
;                 int idx = base + u * nhw + hw; if (idx >= NHR) idx = NHR - 1;
;                 int row, hh; if (idx < NTOK * 10) { row = idx / 10; hh = idx - row * 10; } else { const int j = idx - NTOK * 10; row = NTOK + (j >> 1); hh = 8 + (j & 1); }
;                 rows[u] = row; hhs[u] = hh;
;                 const int col0 = hh < 8 ? hh * 128 : C_AK + (hh - 8) * 128;
;                 const bf16_t* pr = proj + (size_t)row * INCP + col0 + i;
;                 xv[u][0] = bf2f(pr[0]); xv[u][1] = bf2f(pr[32]); xv[u][2] = bf2f(pr[64]); xv[u][3] = bf2f(pr[96]);
;             }
; #pragma unroll
;             for (int u = 0; u < 4; ++u) {
;                 const int row = rows[u], hh = hhs[u];
;                 float x0 = xv[u][0], x1 = xv[u][1], x2 = xv[u][2], x3 = xv[u][3];
;                 float ss = x0 * x0 + x1 * x1 + x2 * x2 + x3 * x3;
; #pragma unroll
;                 for (int o = 1; o < 32; o <<= 1) ss += __shfl_xor(ss, o);
;                 const float rstd = rsqrtf(ss * (1.f / 128.f) + 1e-6f);
;                 if (hh < 8) { x0 *= rstd * gq0; x1 *= rstd * gq1; x2 *= rstd * gq2; x3 *= rstd * gq3; }
;                 else { x0 *= rstd * gk0; x1 *= rstd * gk1; x2 *= rstd * gk2; x3 *= rstd * gk3; }
;                 if (row < NTOK) {
;                     const int t = row & 2047, rr = t >> 6, cc = t & 63;
;                     float sr, cr, sc_, cc_; sincosf((float)rr * invf, &sr, &cr); sincosf((float)cc * invf, &sc_, &cc_);
;                     const float y0 = x0 * cr - x1 * sr, y1 = x1 * cr + x0 * sr, y2 = x2 * cc_ - x3 * sc_, y3 = x3 * cc_ + x2 * sc_;
;                     x0 = y0; x1 = y1; x2 = y2; x3 = y3;
;                 }
;                 bf16_t* op;
;                 if (hh < 8) { const int b = row >> 11, t = row & 2047; const float qs = QSCALE * LOG2E; x0 *= qs; x1 *= qs; x2 *= qs; x3 *= qs;
;                     op = Qp + ((size_t)(b * 8 + hh) * SEQ + t) * 128 + i; }
;                 else { int b, pos; if (row < NTOK) { b = row >> 11; pos = CTXL + (row & 2047); } else { b = (row - NTOK) >> 8; pos = (row - NTOK) & 255; }
	v_add_u32_e32 v43, s0, v129
	v_min_u32_e32 v145, 0x28fff, v43
	v_mul_hi_u32 v154, v145, s98
	v_add_u32_e32 v155, 0xfffd8000, v145
	v_lshrrev_b32_e32 v154, 3, v154
	v_lshrrev_b32_e32 v156, 1, v155
	v_and_b32_e32 v155, 1, v155
	v_mul_u32_u24_e32 v157, 10, v154
	v_add_u32_e32 v156, 0x4000, v156
	v_add_u32_e32 v155, 8, v155
	v_sub_u32_e32 v157, v145, v157
	v_cmp_gt_u32_e32 vcc, 0x28000, v145
	s_nop 1
	v_cndmask_b32_e32 v36, v156, v154, vcc
	v_cndmask_b32_e32 v37, v155, v157, vcc
	v_and_b32_e32 v146, 0x7ff, v36
	v_mul_u32_u24_e32 v147, 0x2600, v36
	v_lshl_add_u32 v147, v37, 8, v147
	v_add_u32_e32 v147, v147, v128
	global_load_ushort v39, v147, s[18:19]
	global_load_ushort v40, v147, s[18:19] offset:64
	global_load_ushort v41, v147, s[18:19] offset:128
	global_load_ushort v42, v147, s[18:19] offset:192
	v_lshrrev_b32_e32 v154, 6, v146
	v_and_b32_e32 v155, 63, v146
	v_lshl_add_u32 v154, v154, 8, v130
	v_lshl_add_u32 v155, v155, 8, v130
	ds_read_b64 v[32:33], v154
	ds_read_b64 v[34:35], v155
	v_lshrrev_b32_e32 v154, 11, v36
	v_add_u32_e32 v155, 0xffffc000, v36
	v_lshrrev_b32_e32 v155, 8, v155
	v_add_u32_e32 v156, 0x100, v146
	v_and_b32_e32 v157, 0xff, v36
	v_cmp_gt_u32_e32 vcc, 0x4000, v36
	v_lshl_add_u32 v38, v154, 3, v37
	v_lshlrev_b32_e32 v38, 19, v38
	v_cndmask_b32_e32 v155, v155, v154, vcc
	v_cndmask_b32_e32 v156, v157, v156, vcc
	v_lshl_add_u32 v38, v146, 8, v38
	v_lshl_add_u32 v155, v155, 1, v37
	v_add_u32_e32 v155, -8, v155
	v_mul_u32_u24_e32 v155, 0x900, v155
	v_add_u32_e32 v155, v155, v156
	v_lshlrev_b32_e32 v155, 8, v155
	v_add_u32_e32 v155, 0x2000000, v155
	v_cmp_gt_u32_e32 vcc, 8, v37
	s_nop 1
	v_cndmask_b32_e32 v38, v155, v38, vcc
	v_add_u32_e32 v38, v38, v128
	s_mul_i32 s44, s1, 1
	s_add_i32 s44, s44, s0
	v_add_u32_e32 v55, s44, v129
	v_min_u32_e32 v158, 0x28fff, v55
	v_mul_hi_u32 v167, v158, s98
	v_add_u32_e32 v168, 0xfffd8000, v158
	v_lshrrev_b32_e32 v167, 3, v167
	v_lshrrev_b32_e32 v169, 1, v168
	v_and_b32_e32 v168, 1, v168
	v_mul_u32_u24_e32 v170, 10, v167
	v_add_u32_e32 v169, 0x4000, v169
	v_add_u32_e32 v168, 8, v168
	v_sub_u32_e32 v170, v158, v170
	v_cmp_gt_u32_e32 vcc, 0x28000, v158
	s_nop 1
	v_cndmask_b32_e32 v48, v169, v167, vcc
	v_cndmask_b32_e32 v49, v168, v170, vcc
	v_and_b32_e32 v159, 0x7ff, v48
	v_mul_u32_u24_e32 v160, 0x2600, v48
	v_lshl_add_u32 v160, v49, 8, v160
	v_add_u32_e32 v160, v160, v128
	global_load_ushort v51, v160, s[18:19]
	global_load_ushort v52, v160, s[18:19] offset:64
	global_load_ushort v53, v160, s[18:19] offset:128
	global_load_ushort v54, v160, s[18:19] offset:192
	v_lshrrev_b32_e32 v167, 6, v159
	v_and_b32_e32 v168, 63, v159
	v_lshl_add_u32 v167, v167, 8, v130
	v_lshl_add_u32 v168, v168, 8, v130
	ds_read_b64 v[44:45], v167
	ds_read_b64 v[46:47], v168
	v_lshrrev_b32_e32 v167, 11, v48
	v_add_u32_e32 v168, 0xffffc000, v48
	v_lshrrev_b32_e32 v168, 8, v168
	v_add_u32_e32 v169, 0x100, v159
	v_and_b32_e32 v170, 0xff, v48
	v_cmp_gt_u32_e32 vcc, 0x4000, v48
	v_lshl_add_u32 v50, v167, 3, v49
	v_lshlrev_b32_e32 v50, 19, v50
	v_cndmask_b32_e32 v168, v168, v167, vcc
	v_cndmask_b32_e32 v169, v170, v169, vcc
	v_lshl_add_u32 v50, v159, 8, v50
	v_lshl_add_u32 v168, v168, 1, v49
	v_add_u32_e32 v168, -8, v168
	v_mul_u32_u24_e32 v168, 0x900, v168
	v_add_u32_e32 v168, v168, v169
	v_lshlrev_b32_e32 v168, 8, v168
	v_add_u32_e32 v168, 0x2000000, v168
	v_cmp_gt_u32_e32 vcc, 8, v49
	s_nop 1
	v_cndmask_b32_e32 v50, v168, v50, vcc
	v_add_u32_e32 v50, v50, v128
	s_mul_i32 s44, s1, 2
	s_add_i32 s44, s44, s0
	v_add_u32_e32 v67, s44, v129
	v_min_u32_e32 v171, 0x28fff, v67
	v_mul_hi_u32 v180, v171, s98
	v_add_u32_e32 v181, 0xfffd8000, v171
	v_lshrrev_b32_e32 v180, 3, v180
	v_lshrrev_b32_e32 v182, 1, v181
	v_and_b32_e32 v181, 1, v181
	v_mul_u32_u24_e32 v183, 10, v180
	v_add_u32_e32 v182, 0x4000, v182
	v_add_u32_e32 v181, 8, v181
	v_sub_u32_e32 v183, v171, v183
	v_cmp_gt_u32_e32 vcc, 0x28000, v171
	s_nop 1
	v_cndmask_b32_e32 v60, v182, v180, vcc
	v_cndmask_b32_e32 v61, v181, v183, vcc
	v_and_b32_e32 v172, 0x7ff, v60
	v_mul_u32_u24_e32 v173, 0x2600, v60
	v_lshl_add_u32 v173, v61, 8, v173
	v_add_u32_e32 v173, v173, v128
	global_load_ushort v63, v173, s[18:19]
	global_load_ushort v64, v173, s[18:19] offset:64
	global_load_ushort v65, v173, s[18:19] offset:128
	global_load_ushort v66, v173, s[18:19] offset:192
	v_lshrrev_b32_e32 v180, 6, v172
	v_and_b32_e32 v181, 63, v172
	v_lshl_add_u32 v180, v180, 8, v130
	v_lshl_add_u32 v181, v181, 8, v130
	ds_read_b64 v[56:57], v180
	ds_read_b64 v[58:59], v181
	v_lshrrev_b32_e32 v180, 11, v60
	v_add_u32_e32 v181, 0xffffc000, v60
	v_lshrrev_b32_e32 v181, 8, v181
	v_add_u32_e32 v182, 0x100, v172
	v_and_b32_e32 v183, 0xff, v60
	v_cmp_gt_u32_e32 vcc, 0x4000, v60
	v_lshl_add_u32 v62, v180, 3, v61
	v_lshlrev_b32_e32 v62, 19, v62
	v_cndmask_b32_e32 v181, v181, v180, vcc
	v_cndmask_b32_e32 v182, v183, v182, vcc
	v_lshl_add_u32 v62, v172, 8, v62
	v_lshl_add_u32 v181, v181, 1, v61
	v_add_u32_e32 v181, -8, v181
	v_mul_u32_u24_e32 v181, 0x900, v181
	v_add_u32_e32 v181, v181, v182
	v_lshlrev_b32_e32 v181, 8, v181
	v_add_u32_e32 v181, 0x2000000, v181
	v_cmp_gt_u32_e32 vcc, 8, v61
	s_nop 1
	v_cndmask_b32_e32 v62, v181, v62, vcc
	v_add_u32_e32 v62, v62, v128
	s_mul_i32 s44, s1, 3
	s_add_i32 s44, s44, s0
	v_add_u32_e32 v79, s44, v129
	v_min_u32_e32 v184, 0x28fff, v79
	v_mul_hi_u32 v193, v184, s98
	v_add_u32_e32 v194, 0xfffd8000, v184
	v_lshrrev_b32_e32 v193, 3, v193
	v_lshrrev_b32_e32 v195, 1, v194
	v_and_b32_e32 v194, 1, v194
	v_mul_u32_u24_e32 v196, 10, v193
	v_add_u32_e32 v195, 0x4000, v195
	v_add_u32_e32 v194, 8, v194
	v_sub_u32_e32 v196, v184, v196
	v_cmp_gt_u32_e32 vcc, 0x28000, v184
	s_nop 1
; __device__ __forceinline__ void prep_phase(const Params& P, LAS unsigned char* lds) {
;     ...
;         for (int base = 0; base < NHR; base += 4 * nhw) {
;             float xv[4][4]; int rows[4], hhs[4];
; #pragma unroll
;             for (int u = 0; u < 4; ++u) {
;                 int idx = base + u * nhw + hw; if (idx >= NHR) idx = NHR - 1;
;                 int row, hh; if (idx < NTOK * 10) { row = idx / 10; hh = idx - row * 10; } else { const int j = idx - NTOK * 10; row = NTOK + (j >> 1); hh = 8 + (j & 1); }
;                 rows[u] = row; hhs[u] = hh;
;                 const int col0 = hh < 8 ? hh * 128 : C_AK + (hh - 8) * 128;
;                 const bf16_t* pr = proj + (size_t)row * INCP + col0 + i;
;                 xv[u][0] = bf2f(pr[0]); xv[u][1] = bf2f(pr[32]); xv[u][2] = bf2f(pr[64]); xv[u][3] = bf2f(pr[96]);
;             }
; #pragma unroll
;             for (int u = 0; u < 4; ++u) {
;                 const int row = rows[u], hh = hhs[u];
;                 float x0 = xv[u][0], x1 = xv[u][1], x2 = xv[u][2], x3 = xv[u][3];
;                 float ss = x0 * x0 + x1 * x1 + x2 * x2 + x3 * x3;
; #pragma unroll
;                 for (int o = 1; o < 32; o <<= 1) ss += __shfl_xor(ss, o);
;                 const float rstd = rsqrtf(ss * (1.f / 128.f) + 1e-6f);
;                 if (hh < 8) { x0 *= rstd * gq0; x1 *= rstd * gq1; x2 *= rstd * gq2; x3 *= rstd * gq3; }
;                 else { x0 *= rstd * gk0; x1 *= rstd * gk1; x2 *= rstd * gk2; x3 *= rstd * gk3; }
;                 if (row < NTOK) {
;                     const int t = row & 2047, rr = t >> 6, cc = t & 63;
;                     float sr, cr, sc_, cc_; sincosf((float)rr * invf, &sr, &cr); sincosf((float)cc * invf, &sc_, &cc_);
;                     const float y0 = x0 * cr - x1 * sr, y1 = x1 * cr + x0 * sr, y2 = x2 * cc_ - x3 * sc_, y3 = x3 * cc_ + x2 * sc_;
;                     x0 = y0; x1 = y1; x2 = y2; x3 = y3;
;                 }
;                 bf16_t* op;
;                 if (hh < 8) { const int b = row >> 11, t = row & 2047; const float qs = QSCALE * LOG2E; x0 *= qs; x1 *= qs; x2 *= qs; x3 *= qs;
;                     op = Qp + ((size_t)(b * 8 + hh) * SEQ + t) * 128 + i; }
;                 else { int b, pos; if (row < NTOK) { b = row >> 11; pos = CTXL + (row & 2047); } else { b = (row - NTOK) >> 8; pos = (row - NTOK) & 255; }
	v_cndmask_b32_e32 v72, v195, v193, vcc
	v_cndmask_b32_e32 v73, v194, v196, vcc
	v_and_b32_e32 v185, 0x7ff, v72
	v_mul_u32_u24_e32 v186, 0x2600, v72
	v_lshl_add_u32 v186, v73, 8, v186
	v_add_u32_e32 v186, v186, v128
	global_load_ushort v75, v186, s[18:19]
	global_load_ushort v76, v186, s[18:19] offset:64
	global_load_ushort v77, v186, s[18:19] offset:128
	global_load_ushort v78, v186, s[18:19] offset:192
	v_lshrrev_b32_e32 v193, 6, v185
	v_and_b32_e32 v194, 63, v185
	v_lshl_add_u32 v193, v193, 8, v130
	v_lshl_add_u32 v194, v194, 8, v130
	ds_read_b64 v[68:69], v193
	ds_read_b64 v[70:71], v194
	v_lshrrev_b32_e32 v193, 11, v72
	v_add_u32_e32 v194, 0xffffc000, v72
	v_lshrrev_b32_e32 v194, 8, v194
	v_add_u32_e32 v195, 0x100, v185
	v_and_b32_e32 v196, 0xff, v72
	v_cmp_gt_u32_e32 vcc, 0x4000, v72
	v_lshl_add_u32 v74, v193, 3, v73
	v_lshlrev_b32_e32 v74, 19, v74
	v_cndmask_b32_e32 v194, v194, v193, vcc
	v_cndmask_b32_e32 v195, v196, v195, vcc
	v_lshl_add_u32 v74, v185, 8, v74
	v_lshl_add_u32 v194, v194, 1, v73
	v_add_u32_e32 v194, -8, v194
	v_mul_u32_u24_e32 v194, 0x900, v194
	v_add_u32_e32 v194, v194, v195
	v_lshlrev_b32_e32 v194, 8, v194
	v_add_u32_e32 v194, 0x2000000, v194
	v_cmp_gt_u32_e32 vcc, 8, v73
	s_nop 1
	v_cndmask_b32_e32 v74, v194, v74, vcc
	v_add_u32_e32 v74, v74, v128
	s_add_i32 s45, s0, s99
	v_add_u32_e32 v91, s45, v129
	v_min_u32_e32 v145, 0x28fff, v91
	v_mul_hi_u32 v154, v145, s98
	v_add_u32_e32 v155, 0xfffd8000, v145
	v_lshrrev_b32_e32 v154, 3, v154
	v_lshrrev_b32_e32 v156, 1, v155
	v_and_b32_e32 v155, 1, v155
	v_mul_u32_u24_e32 v157, 10, v154
	v_add_u32_e32 v156, 0x4000, v156
	v_add_u32_e32 v155, 8, v155
	v_sub_u32_e32 v157, v145, v157
	v_cmp_gt_u32_e32 vcc, 0x28000, v145
	s_nop 1
	v_cndmask_b32_e32 v84, v156, v154, vcc
	v_cndmask_b32_e32 v85, v155, v157, vcc
	v_and_b32_e32 v146, 0x7ff, v84
	v_mul_u32_u24_e32 v147, 0x2600, v84
	v_lshl_add_u32 v147, v85, 8, v147
	v_add_u32_e32 v147, v147, v128
	global_load_ushort v87, v147, s[18:19]
	global_load_ushort v88, v147, s[18:19] offset:64
	global_load_ushort v89, v147, s[18:19] offset:128
	global_load_ushort v90, v147, s[18:19] offset:192
	v_lshrrev_b32_e32 v154, 6, v146
	v_and_b32_e32 v155, 63, v146
	v_lshl_add_u32 v154, v154, 8, v130
	v_lshl_add_u32 v155, v155, 8, v130
	ds_read_b64 v[80:81], v154
	ds_read_b64 v[82:83], v155
	v_lshrrev_b32_e32 v154, 11, v84
	v_add_u32_e32 v155, 0xffffc000, v84
	v_lshrrev_b32_e32 v155, 8, v155
	v_add_u32_e32 v156, 0x100, v146
	v_and_b32_e32 v157, 0xff, v84
	v_cmp_gt_u32_e32 vcc, 0x4000, v84
	v_lshl_add_u32 v86, v154, 3, v85
	v_lshlrev_b32_e32 v86, 19, v86
	v_cndmask_b32_e32 v155, v155, v154, vcc
	v_cndmask_b32_e32 v156, v157, v156, vcc
	v_lshl_add_u32 v86, v146, 8, v86
	v_lshl_add_u32 v155, v155, 1, v85
	v_add_u32_e32 v155, -8, v155
	v_mul_u32_u24_e32 v155, 0x900, v155
	v_add_u32_e32 v155, v155, v156
	v_lshlrev_b32_e32 v155, 8, v155
	v_add_u32_e32 v155, 0x2000000, v155
	v_cmp_gt_u32_e32 vcc, 8, v85
	s_nop 1
	v_cndmask_b32_e32 v86, v155, v86, vcc
	v_add_u32_e32 v86, v86, v128
	s_mul_i32 s44, s1, 1
	s_add_i32 s44, s44, s45
	v_add_u32_e32 v103, s44, v129
	v_min_u32_e32 v158, 0x28fff, v103
	v_mul_hi_u32 v167, v158, s98
	v_add_u32_e32 v168, 0xfffd8000, v158
	v_lshrrev_b32_e32 v167, 3, v167
	v_lshrrev_b32_e32 v169, 1, v168
	v_and_b32_e32 v168, 1, v168
	v_mul_u32_u24_e32 v170, 10, v167
	v_add_u32_e32 v169, 0x4000, v169
	v_add_u32_e32 v168, 8, v168
	v_sub_u32_e32 v170, v158, v170
	v_cmp_gt_u32_e32 vcc, 0x28000, v158
	s_nop 1
	v_cndmask_b32_e32 v96, v169, v167, vcc
	v_cndmask_b32_e32 v97, v168, v170, vcc
	v_and_b32_e32 v159, 0x7ff, v96
	v_mul_u32_u24_e32 v160, 0x2600, v96
	v_lshl_add_u32 v160, v97, 8, v160
	v_add_u32_e32 v160, v160, v128
	global_load_ushort v99, v160, s[18:19]
	global_load_ushort v100, v160, s[18:19] offset:64
	global_load_ushort v101, v160, s[18:19] offset:128
	global_load_ushort v102, v160, s[18:19] offset:192
	v_lshrrev_b32_e32 v167, 6, v159
	v_and_b32_e32 v168, 63, v159
	v_lshl_add_u32 v167, v167, 8, v130
	v_lshl_add_u32 v168, v168, 8, v130
	ds_read_b64 v[92:93], v167
	ds_read_b64 v[94:95], v168
	v_lshrrev_b32_e32 v167, 11, v96
	v_add_u32_e32 v168, 0xffffc000, v96
	v_lshrrev_b32_e32 v168, 8, v168
	v_add_u32_e32 v169, 0x100, v159
	v_and_b32_e32 v170, 0xff, v96
	v_cmp_gt_u32_e32 vcc, 0x4000, v96
	v_lshl_add_u32 v98, v167, 3, v97
	v_lshlrev_b32_e32 v98, 19, v98
	v_cndmask_b32_e32 v168, v168, v167, vcc
	v_cndmask_b32_e32 v169, v170, v169, vcc
	v_lshl_add_u32 v98, v159, 8, v98
	v_lshl_add_u32 v168, v168, 1, v97
	v_add_u32_e32 v168, -8, v168
	v_mul_u32_u24_e32 v168, 0x900, v168
	v_add_u32_e32 v168, v168, v169
	v_lshlrev_b32_e32 v168, 8, v168
	v_add_u32_e32 v168, 0x2000000, v168
	v_cmp_gt_u32_e32 vcc, 8, v97
	s_nop 1
	v_cndmask_b32_e32 v98, v168, v98, vcc
	v_add_u32_e32 v98, v98, v128
	s_mul_i32 s44, s1, 2
	s_add_i32 s44, s44, s45
	v_add_u32_e32 v115, s44, v129
	v_min_u32_e32 v171, 0x28fff, v115
	v_mul_hi_u32 v180, v171, s98
	v_add_u32_e32 v181, 0xfffd8000, v171
	v_lshrrev_b32_e32 v180, 3, v180
	v_lshrrev_b32_e32 v182, 1, v181
	v_and_b32_e32 v181, 1, v181
	v_mul_u32_u24_e32 v183, 10, v180
	v_add_u32_e32 v182, 0x4000, v182
	v_add_u32_e32 v181, 8, v181
	v_sub_u32_e32 v183, v171, v183
	v_cmp_gt_u32_e32 vcc, 0x28000, v171
	s_nop 1
	v_cndmask_b32_e32 v108, v182, v180, vcc
	v_cndmask_b32_e32 v109, v181, v183, vcc
	v_and_b32_e32 v172, 0x7ff, v108
	v_mul_u32_u24_e32 v173, 0x2600, v108
	v_lshl_add_u32 v173, v109, 8, v173
	v_add_u32_e32 v173, v173, v128
	global_load_ushort v111, v173, s[18:19]
	global_load_ushort v112, v173, s[18:19] offset:64
	global_load_ushort v113, v173, s[18:19] offset:128
	global_load_ushort v114, v173, s[18:19] offset:192
; __device__ __forceinline__ float bf2f(bf16_t h) { return __uint_as_float(((unsigned)h) << 16); }
; __device__ __forceinline__ void prep_phase(const Params& P, LAS unsigned char* lds) {
;     ...
;                 int idx = base + u * nhw + hw; if (idx >= NHR) idx = NHR - 1;
;                 int row, hh; if (idx < NTOK * 10) { row = idx / 10; hh = idx - row * 10; } else { const int j = idx - NTOK * 10; row = NTOK + (j >> 1); hh = 8 + (j & 1); }
;                 rows[u] = row; hhs[u] = hh;
;                 const int col0 = hh < 8 ? hh * 128 : C_AK + (hh - 8) * 128;
;                 const bf16_t* pr = proj + (size_t)row * INCP + col0 + i;
;                 xv[u][0] = bf2f(pr[0]); xv[u][1] = bf2f(pr[32]); xv[u][2] = bf2f(pr[64]); xv[u][3] = bf2f(pr[96]);
;             }
; #pragma unroll
;             for (int u = 0; u < 4; ++u) {
;                 const int row = rows[u], hh = hhs[u];
;                 float x0 = xv[u][0], x1 = xv[u][1], x2 = xv[u][2], x3 = xv[u][3];
;                 float ss = x0 * x0 + x1 * x1 + x2 * x2 + x3 * x3;
; #pragma unroll
;                 for (int o = 1; o < 32; o <<= 1) ss += __shfl_xor(ss, o);
;                 const float rstd = rsqrtf(ss * (1.f / 128.f) + 1e-6f);
	v_lshrrev_b32_e32 v180, 6, v172
	v_and_b32_e32 v181, 63, v172
	v_lshl_add_u32 v180, v180, 8, v130
	v_lshl_add_u32 v181, v181, 8, v130
	ds_read_b64 v[104:105], v180
	ds_read_b64 v[106:107], v181
	v_lshrrev_b32_e32 v180, 11, v108
	v_add_u32_e32 v181, 0xffffc000, v108
	v_lshrrev_b32_e32 v181, 8, v181
	v_add_u32_e32 v182, 0x100, v172
	v_and_b32_e32 v183, 0xff, v108
	v_cmp_gt_u32_e32 vcc, 0x4000, v108
	v_lshl_add_u32 v110, v180, 3, v109
	v_lshlrev_b32_e32 v110, 19, v110
	v_cndmask_b32_e32 v181, v181, v180, vcc
	v_cndmask_b32_e32 v182, v183, v182, vcc
	v_lshl_add_u32 v110, v172, 8, v110
	v_lshl_add_u32 v181, v181, 1, v109
	v_add_u32_e32 v181, -8, v181
	v_mul_u32_u24_e32 v181, 0x900, v181
	v_add_u32_e32 v181, v181, v182
	v_lshlrev_b32_e32 v181, 8, v181
	v_add_u32_e32 v181, 0x2000000, v181
	v_cmp_gt_u32_e32 vcc, 8, v109
	s_nop 1
	v_cndmask_b32_e32 v110, v181, v110, vcc
	v_add_u32_e32 v110, v110, v128
	s_mul_i32 s44, s1, 3
	s_add_i32 s44, s44, s45
	v_add_u32_e32 v127, s44, v129
	v_min_u32_e32 v184, 0x28fff, v127
	v_mul_hi_u32 v193, v184, s98
	v_add_u32_e32 v194, 0xfffd8000, v184
	v_lshrrev_b32_e32 v193, 3, v193
	v_lshrrev_b32_e32 v195, 1, v194
	v_and_b32_e32 v194, 1, v194
	v_mul_u32_u24_e32 v196, 10, v193
	v_add_u32_e32 v195, 0x4000, v195
	v_add_u32_e32 v194, 8, v194
	v_sub_u32_e32 v196, v184, v196
	v_cmp_gt_u32_e32 vcc, 0x28000, v184
	s_nop 1
	v_cndmask_b32_e32 v120, v195, v193, vcc
	v_cndmask_b32_e32 v121, v194, v196, vcc
	v_and_b32_e32 v185, 0x7ff, v120
	v_mul_u32_u24_e32 v186, 0x2600, v120
	v_lshl_add_u32 v186, v121, 8, v186
	v_add_u32_e32 v186, v186, v128
	global_load_ushort v123, v186, s[18:19]
	global_load_ushort v124, v186, s[18:19] offset:64
	global_load_ushort v125, v186, s[18:19] offset:128
	global_load_ushort v126, v186, s[18:19] offset:192
	v_lshrrev_b32_e32 v193, 6, v185
	v_and_b32_e32 v194, 63, v185
	v_lshl_add_u32 v193, v193, 8, v130
	v_lshl_add_u32 v194, v194, 8, v130
	ds_read_b64 v[116:117], v193
	ds_read_b64 v[118:119], v194
	v_lshrrev_b32_e32 v193, 11, v120
	v_add_u32_e32 v194, 0xffffc000, v120
	v_lshrrev_b32_e32 v194, 8, v194
	v_add_u32_e32 v195, 0x100, v185
	v_and_b32_e32 v196, 0xff, v120
	v_cmp_gt_u32_e32 vcc, 0x4000, v120
	v_lshl_add_u32 v122, v193, 3, v121
	v_lshlrev_b32_e32 v122, 19, v122
	v_cndmask_b32_e32 v194, v194, v193, vcc
	v_cndmask_b32_e32 v195, v196, v195, vcc
	v_lshl_add_u32 v122, v185, 8, v122
	v_lshl_add_u32 v194, v194, 1, v121
	v_add_u32_e32 v194, -8, v194
	v_mul_u32_u24_e32 v194, 0x900, v194
	v_add_u32_e32 v194, v194, v195
	v_lshlrev_b32_e32 v194, 8, v194
	v_add_u32_e32 v194, 0x2000000, v194
	v_cmp_gt_u32_e32 vcc, 8, v121
	s_nop 1
	v_cndmask_b32_e32 v122, v194, v122, vcc
	v_add_u32_e32 v122, v122, v128
	s_waitcnt vmcnt(16) lgkmcnt(0)
	v_lshlrev_b32_e32 v39, 16, v39
	v_lshlrev_b32_e32 v40, 16, v40
	v_lshlrev_b32_e32 v41, 16, v41
	v_lshlrev_b32_e32 v42, 16, v42
	v_mul_f32_e32 v154, v39, v39
	v_mul_f32_e32 v155, v40, v40
	v_mul_f32_e32 v156, v41, v41
	v_mul_f32_e32 v157, v42, v42
	v_add_f32_e32 v148, v154, v155
	v_add_f32_e32 v148, v156, v148
	v_add_f32_e32 v148, v157, v148
	v_lshlrev_b32_e32 v51, 16, v51
	v_lshlrev_b32_e32 v52, 16, v52
	v_lshlrev_b32_e32 v53, 16, v53
	v_lshlrev_b32_e32 v54, 16, v54
	v_mul_f32_e32 v167, v51, v51
	v_mul_f32_e32 v168, v52, v52
	v_mul_f32_e32 v169, v53, v53
	v_mul_f32_e32 v170, v54, v54
	v_add_f32_e32 v161, v167, v168
	v_add_f32_e32 v161, v169, v161
	v_add_f32_e32 v161, v170, v161
	v_lshlrev_b32_e32 v63, 16, v63
	v_lshlrev_b32_e32 v64, 16, v64
	v_lshlrev_b32_e32 v65, 16, v65
	v_lshlrev_b32_e32 v66, 16, v66
	v_mul_f32_e32 v180, v63, v63
	v_mul_f32_e32 v181, v64, v64
	v_mul_f32_e32 v182, v65, v65
	v_mul_f32_e32 v183, v66, v66
	v_add_f32_e32 v174, v180, v181
	v_add_f32_e32 v174, v182, v174
	v_add_f32_e32 v174, v183, v174
	v_lshlrev_b32_e32 v75, 16, v75
	v_lshlrev_b32_e32 v76, 16, v76
	v_lshlrev_b32_e32 v77, 16, v77
	v_lshlrev_b32_e32 v78, 16, v78
	v_mul_f32_e32 v193, v75, v75
	v_mul_f32_e32 v194, v76, v76
	v_mul_f32_e32 v195, v77, v77
	v_mul_f32_e32 v196, v78, v78
	v_add_f32_e32 v187, v193, v194
	v_add_f32_e32 v187, v195, v187
	v_add_f32_e32 v187, v196, v187
	s_nop 1
	v_add_f32_dpp v149, v148, v148 quad_perm:[1,0,3,2] row_mask:0xf bank_mask:0xf
	v_add_f32_dpp v162, v161, v161 quad_perm:[1,0,3,2] row_mask:0xf bank_mask:0xf
	v_add_f32_dpp v175, v174, v174 quad_perm:[1,0,3,2] row_mask:0xf bank_mask:0xf
	v_add_f32_dpp v188, v187, v187 quad_perm:[1,0,3,2] row_mask:0xf bank_mask:0xf
	v_mov_b32_e32 v148, v149
	v_mov_b32_e32 v161, v162
	v_mov_b32_e32 v174, v175
	v_mov_b32_e32 v187, v188
	s_nop 1
	v_add_f32_dpp v149, v148, v148 quad_perm:[2,3,0,1] row_mask:0xf bank_mask:0xf
	v_add_f32_dpp v162, v161, v161 quad_perm:[2,3,0,1] row_mask:0xf bank_mask:0xf
	v_add_f32_dpp v175, v174, v174 quad_perm:[2,3,0,1] row_mask:0xf bank_mask:0xf
	v_add_f32_dpp v188, v187, v187 quad_perm:[2,3,0,1] row_mask:0xf bank_mask:0xf
	v_mov_b32_e32 v148, v149
	v_mov_b32_e32 v161, v162
	v_mov_b32_e32 v174, v175
	v_mov_b32_e32 v187, v188
	s_nop 1
	v_add_f32_dpp v149, v148, v148 row_half_mirror row_mask:0xf bank_mask:0xf
	v_add_f32_dpp v162, v161, v161 row_half_mirror row_mask:0xf bank_mask:0xf
	v_add_f32_dpp v175, v174, v174 row_half_mirror row_mask:0xf bank_mask:0xf
	v_add_f32_dpp v188, v187, v187 row_half_mirror row_mask:0xf bank_mask:0xf
	v_mov_b32_e32 v148, v149
	v_mov_b32_e32 v161, v162
	v_mov_b32_e32 v174, v175
	v_mov_b32_e32 v187, v188
	s_nop 1
	v_add_f32_dpp v149, v148, v148 row_mirror row_mask:0xf bank_mask:0xf
	v_add_f32_dpp v162, v161, v161 row_mirror row_mask:0xf bank_mask:0xf
	v_add_f32_dpp v175, v174, v174 row_mirror row_mask:0xf bank_mask:0xf
	v_add_f32_dpp v188, v187, v187 row_mirror row_mask:0xf bank_mask:0xf
	v_mov_b32_e32 v148, v149
	v_mov_b32_e32 v161, v162
	v_mov_b32_e32 v174, v175
	v_mov_b32_e32 v187, v188
	ds_swizzle_b32 v149, v148 offset:swizzle(SWAP,16)
	ds_swizzle_b32 v162, v161 offset:swizzle(SWAP,16)
	ds_swizzle_b32 v175, v174 offset:swizzle(SWAP,16)
	ds_swizzle_b32 v188, v187 offset:swizzle(SWAP,16)
	s_waitcnt lgkmcnt(0)
; __device__ __forceinline__ bf16_t f2bf1(float x) { return (bf16_t)(cvt_pk_bf16(x, 0.f) & 0xffffu); }
; __device__ __forceinline__ void prep_phase(const Params& P, LAS unsigned char* lds) {
;     ...
;                 const int row = rows[u], hh = hhs[u];
;                 float x0 = xv[u][0], x1 = xv[u][1], x2 = xv[u][2], x3 = xv[u][3];
;                 float ss = x0 * x0 + x1 * x1 + x2 * x2 + x3 * x3;
; #pragma unroll
;                 for (int o = 1; o < 32; o <<= 1) ss += __shfl_xor(ss, o);
;                 const float rstd = rsqrtf(ss * (1.f / 128.f) + 1e-6f);
;                 if (hh < 8) { x0 *= rstd * gq0; x1 *= rstd * gq1; x2 *= rstd * gq2; x3 *= rstd * gq3; }
;                 else { x0 *= rstd * gk0; x1 *= rstd * gk1; x2 *= rstd * gk2; x3 *= rstd * gk3; }
;                 if (row < NTOK) {
;                     const int t = row & 2047, rr = t >> 6, cc = t & 63;
;                     float sr, cr, sc_, cc_; sincosf((float)rr * invf, &sr, &cr); sincosf((float)cc * invf, &sc_, &cc_);
;                     const float y0 = x0 * cr - x1 * sr, y1 = x1 * cr + x0 * sr, y2 = x2 * cc_ - x3 * sc_, y3 = x3 * cc_ + x2 * sc_;
;                     x0 = y0; x1 = y1; x2 = y2; x3 = y3;
;                 }
;                 bf16_t* op;
;                 if (hh < 8) { const int b = row >> 11, t = row & 2047; const float qs = QSCALE * LOG2E; x0 *= qs; x1 *= qs; x2 *= qs; x3 *= qs;
;                     op = Qp + ((size_t)(b * 8 + hh) * SEQ + t) * 128 + i; }
;                 else { int b, pos; if (row < NTOK) { b = row >> 11; pos = CTXL + (row & 2047); } else { b = (row - NTOK) >> 8; pos = (row - NTOK) & 255; }
;                     op = Kp + ((size_t)(b * 2 + (hh - 8)) * KVLEN + pos) * 128 + i; }
;                 if (base + u * nhw + hw < NHR) { op[0] = f2bf1(x0); op[32] = f2bf1(x1); op[64] = f2bf1(x2); op[96] = f2bf1(x3); }
	v_add_f32_e32 v148, v148, v149
	v_add_f32_e32 v161, v161, v162
	v_add_f32_e32 v174, v174, v175
	v_add_f32_e32 v187, v187, v188
	v_fmamk_f32 v148, v148, 0x3c000000, v140
	v_fmamk_f32 v161, v161, 0x3c000000, v140
	v_fmamk_f32 v174, v174, 0x3c000000, v140
	v_fmamk_f32 v187, v187, 0x3c000000, v140
	v_rsq_f32_e32 v148, v148
	v_rsq_f32_e32 v161, v161
	v_rsq_f32_e32 v174, v174
	v_rsq_f32_e32 v187, v187
	v_cmp_gt_u32_e32 vcc, 8, v37
	s_nop 1
	v_cndmask_b32_e32 v154, v136, v132, vcc
	v_cndmask_b32_e32 v155, v137, v133, vcc
	v_cndmask_b32_e32 v156, v138, v134, vcc
	v_cndmask_b32_e32 v157, v139, v135, vcc
	v_mul_f32_e32 v154, v154, v148
	v_mul_f32_e32 v155, v155, v148
	v_mul_f32_e32 v156, v156, v148
	v_mul_f32_e32 v157, v157, v148
	v_mul_f32_e32 v39, v154, v39
	v_mul_f32_e32 v40, v155, v40
	v_mul_f32_e32 v41, v156, v41
	v_mul_f32_e32 v42, v157, v42
	v_mul_f32_e32 v154, v40, v32
	v_mul_f32_e32 v155, v39, v32
	v_mul_f32_e32 v156, v42, v34
	v_mul_f32_e32 v157, v41, v34
	v_fma_f32 v150, v39, v33, -v154
	v_fma_f32 v151, v40, v33, v155
	v_fma_f32 v152, v41, v35, -v156
	v_fma_f32 v153, v42, v35, v157
	v_cmp_gt_u32_e32 vcc, 0x4000, v36
	s_nop 1
	v_cndmask_b32_e32 v150, v39, v150, vcc
	v_cndmask_b32_e32 v151, v40, v151, vcc
	v_cndmask_b32_e32 v152, v41, v152, vcc
	v_cndmask_b32_e32 v153, v42, v153, vcc
	v_mul_f32_e32 v154, 0x3e0293ee, v150
	v_mul_f32_e32 v155, 0x3e0293ee, v151
	v_mul_f32_e32 v156, 0x3e0293ee, v152
	v_mul_f32_e32 v157, 0x3e0293ee, v153
	v_cmp_gt_u32_e32 vcc, 8, v37
	s_nop 1
	v_cndmask_b32_e32 v150, v150, v154, vcc
	v_cndmask_b32_e32 v151, v151, v155, vcc
	v_cndmask_b32_e32 v152, v152, v156, vcc
	v_cndmask_b32_e32 v153, v153, v157, vcc
	v_cvt_pk_bf16_f32 v150, v150, v150
	v_cvt_pk_bf16_f32 v151, v151, v151
	v_cvt_pk_bf16_f32 v152, v152, v152
	v_cvt_pk_bf16_f32 v153, v153, v153
	v_cmp_gt_u32_e32 vcc, 0x29000, v43
	s_nop 1
	s_mov_b64 exec, vcc
	global_store_short v38, v150, s[4:5]
	global_store_short v38, v151, s[4:5] offset:64
	global_store_short v38, v152, s[4:5] offset:128
	global_store_short v38, v153, s[4:5] offset:192
	s_mov_b64 exec, -1
	v_cmp_gt_u32_e32 vcc, 8, v49
	s_nop 1
	v_cndmask_b32_e32 v167, v136, v132, vcc
	v_cndmask_b32_e32 v168, v137, v133, vcc
	v_cndmask_b32_e32 v169, v138, v134, vcc
	v_cndmask_b32_e32 v170, v139, v135, vcc
	v_mul_f32_e32 v167, v167, v161
	v_mul_f32_e32 v168, v168, v161
	v_mul_f32_e32 v169, v169, v161
	v_mul_f32_e32 v170, v170, v161
	v_mul_f32_e32 v51, v167, v51
	v_mul_f32_e32 v52, v168, v52
	v_mul_f32_e32 v53, v169, v53
	v_mul_f32_e32 v54, v170, v54
	v_mul_f32_e32 v167, v52, v44
	v_mul_f32_e32 v168, v51, v44
	v_mul_f32_e32 v169, v54, v46
	v_mul_f32_e32 v170, v53, v46
	v_fma_f32 v163, v51, v45, -v167
	v_fma_f32 v164, v52, v45, v168
	v_fma_f32 v165, v53, v47, -v169
	v_fma_f32 v166, v54, v47, v170
	v_cmp_gt_u32_e32 vcc, 0x4000, v48
	s_nop 1
	v_cndmask_b32_e32 v163, v51, v163, vcc
	v_cndmask_b32_e32 v164, v52, v164, vcc
	v_cndmask_b32_e32 v165, v53, v165, vcc
	v_cndmask_b32_e32 v166, v54, v166, vcc
	v_mul_f32_e32 v167, 0x3e0293ee, v163
	v_mul_f32_e32 v168, 0x3e0293ee, v164
	v_mul_f32_e32 v169, 0x3e0293ee, v165
	v_mul_f32_e32 v170, 0x3e0293ee, v166
	v_cmp_gt_u32_e32 vcc, 8, v49
	s_nop 1
	v_cndmask_b32_e32 v163, v163, v167, vcc
	v_cndmask_b32_e32 v164, v164, v168, vcc
	v_cndmask_b32_e32 v165, v165, v169, vcc
	v_cndmask_b32_e32 v166, v166, v170, vcc
	v_cvt_pk_bf16_f32 v163, v163, v163
	v_cvt_pk_bf16_f32 v164, v164, v164
	v_cvt_pk_bf16_f32 v165, v165, v165
	v_cvt_pk_bf16_f32 v166, v166, v166
	v_cmp_gt_u32_e32 vcc, 0x29000, v55
	s_nop 1
	s_mov_b64 exec, vcc
	global_store_short v50, v163, s[4:5]
	global_store_short v50, v164, s[4:5] offset:64
	global_store_short v50, v165, s[4:5] offset:128
	global_store_short v50, v166, s[4:5] offset:192
	s_mov_b64 exec, -1
	v_cmp_gt_u32_e32 vcc, 8, v61
	s_nop 1
	v_cndmask_b32_e32 v180, v136, v132, vcc
	v_cndmask_b32_e32 v181, v137, v133, vcc
	v_cndmask_b32_e32 v182, v138, v134, vcc
	v_cndmask_b32_e32 v183, v139, v135, vcc
	v_mul_f32_e32 v180, v180, v174
	v_mul_f32_e32 v181, v181, v174
	v_mul_f32_e32 v182, v182, v174
	v_mul_f32_e32 v183, v183, v174
	v_mul_f32_e32 v63, v180, v63
	v_mul_f32_e32 v64, v181, v64
	v_mul_f32_e32 v65, v182, v65
	v_mul_f32_e32 v66, v183, v66
	v_mul_f32_e32 v180, v64, v56
	v_mul_f32_e32 v181, v63, v56
	v_mul_f32_e32 v182, v66, v58
	v_mul_f32_e32 v183, v65, v58
	v_fma_f32 v176, v63, v57, -v180
	v_fma_f32 v177, v64, v57, v181
	v_fma_f32 v178, v65, v59, -v182
	v_fma_f32 v179, v66, v59, v183
	v_cmp_gt_u32_e32 vcc, 0x4000, v60
	s_nop 1
	v_cndmask_b32_e32 v176, v63, v176, vcc
	v_cndmask_b32_e32 v177, v64, v177, vcc
	v_cndmask_b32_e32 v178, v65, v178, vcc
	v_cndmask_b32_e32 v179, v66, v179, vcc
	v_mul_f32_e32 v180, 0x3e0293ee, v176
	v_mul_f32_e32 v181, 0x3e0293ee, v177
	v_mul_f32_e32 v182, 0x3e0293ee, v178
	v_mul_f32_e32 v183, 0x3e0293ee, v179
	v_cmp_gt_u32_e32 vcc, 8, v61
	s_nop 1
	v_cndmask_b32_e32 v176, v176, v180, vcc
	v_cndmask_b32_e32 v177, v177, v181, vcc
	v_cndmask_b32_e32 v178, v178, v182, vcc
	v_cndmask_b32_e32 v179, v179, v183, vcc
	v_cvt_pk_bf16_f32 v176, v176, v176
	v_cvt_pk_bf16_f32 v177, v177, v177
	v_cvt_pk_bf16_f32 v178, v178, v178
	v_cvt_pk_bf16_f32 v179, v179, v179
	v_cmp_gt_u32_e32 vcc, 0x29000, v67
	s_nop 1
	s_mov_b64 exec, vcc
	global_store_short v62, v176, s[4:5]
	global_store_short v62, v177, s[4:5] offset:64
	global_store_short v62, v178, s[4:5] offset:128
	global_store_short v62, v179, s[4:5] offset:192
	s_mov_b64 exec, -1
	v_cmp_gt_u32_e32 vcc, 8, v73
	s_nop 1
	v_cndmask_b32_e32 v193, v136, v132, vcc
	v_cndmask_b32_e32 v194, v137, v133, vcc
	v_cndmask_b32_e32 v195, v138, v134, vcc
	v_cndmask_b32_e32 v196, v139, v135, vcc
; __device__ __forceinline__ bf16_t f2bf1(float x) { return (bf16_t)(cvt_pk_bf16(x, 0.f) & 0xffffu); }
; __device__ __forceinline__ void prep_phase(const Params& P, LAS unsigned char* lds) {
;     ...
;                 const int row = rows[u], hh = hhs[u];
;                 float x0 = xv[u][0], x1 = xv[u][1], x2 = xv[u][2], x3 = xv[u][3];
;                 float ss = x0 * x0 + x1 * x1 + x2 * x2 + x3 * x3;
; #pragma unroll
;                 for (int o = 1; o < 32; o <<= 1) ss += __shfl_xor(ss, o);
;                 const float rstd = rsqrtf(ss * (1.f / 128.f) + 1e-6f);
;                 if (hh < 8) { x0 *= rstd * gq0; x1 *= rstd * gq1; x2 *= rstd * gq2; x3 *= rstd * gq3; }
;                 else { x0 *= rstd * gk0; x1 *= rstd * gk1; x2 *= rstd * gk2; x3 *= rstd * gk3; }
;                 if (row < NTOK) {
;                     const int t = row & 2047, rr = t >> 6, cc = t & 63;
;                     float sr, cr, sc_, cc_; sincosf((float)rr * invf, &sr, &cr); sincosf((float)cc * invf, &sc_, &cc_);
;                     const float y0 = x0 * cr - x1 * sr, y1 = x1 * cr + x0 * sr, y2 = x2 * cc_ - x3 * sc_, y3 = x3 * cc_ + x2 * sc_;
;                     x0 = y0; x1 = y1; x2 = y2; x3 = y3;
;                 }
;                 bf16_t* op;
;                 if (hh < 8) { const int b = row >> 11, t = row & 2047; const float qs = QSCALE * LOG2E; x0 *= qs; x1 *= qs; x2 *= qs; x3 *= qs;
;                     op = Qp + ((size_t)(b * 8 + hh) * SEQ + t) * 128 + i; }
;                 else { int b, pos; if (row < NTOK) { b = row >> 11; pos = CTXL + (row & 2047); } else { b = (row - NTOK) >> 8; pos = (row - NTOK) & 255; }
;                     op = Kp + ((size_t)(b * 2 + (hh - 8)) * KVLEN + pos) * 128 + i; }
;                 if (base + u * nhw + hw < NHR) { op[0] = f2bf1(x0); op[32] = f2bf1(x1); op[64] = f2bf1(x2); op[96] = f2bf1(x3); }
;             }
;         }
	v_mul_f32_e32 v193, v193, v187
	v_mul_f32_e32 v194, v194, v187
	v_mul_f32_e32 v195, v195, v187
	v_mul_f32_e32 v196, v196, v187
	v_mul_f32_e32 v75, v193, v75
	v_mul_f32_e32 v76, v194, v76
	v_mul_f32_e32 v77, v195, v77
	v_mul_f32_e32 v78, v196, v78
	v_mul_f32_e32 v193, v76, v68
	v_mul_f32_e32 v194, v75, v68
	v_mul_f32_e32 v195, v78, v70
	v_mul_f32_e32 v196, v77, v70
	v_fma_f32 v189, v75, v69, -v193
	v_fma_f32 v190, v76, v69, v194
	v_fma_f32 v191, v77, v71, -v195
	v_fma_f32 v192, v78, v71, v196
	v_cmp_gt_u32_e32 vcc, 0x4000, v72
	s_nop 1
	v_cndmask_b32_e32 v189, v75, v189, vcc
	v_cndmask_b32_e32 v190, v76, v190, vcc
	v_cndmask_b32_e32 v191, v77, v191, vcc
	v_cndmask_b32_e32 v192, v78, v192, vcc
	v_mul_f32_e32 v193, 0x3e0293ee, v189
	v_mul_f32_e32 v194, 0x3e0293ee, v190
	v_mul_f32_e32 v195, 0x3e0293ee, v191
	v_mul_f32_e32 v196, 0x3e0293ee, v192
	v_cmp_gt_u32_e32 vcc, 8, v73
	s_nop 1
	v_cndmask_b32_e32 v189, v189, v193, vcc
	v_cndmask_b32_e32 v190, v190, v194, vcc
	v_cndmask_b32_e32 v191, v191, v195, vcc
	v_cndmask_b32_e32 v192, v192, v196, vcc
	v_cvt_pk_bf16_f32 v189, v189, v189
	v_cvt_pk_bf16_f32 v190, v190, v190
	v_cvt_pk_bf16_f32 v191, v191, v191
	v_cvt_pk_bf16_f32 v192, v192, v192
	v_cmp_gt_u32_e32 vcc, 0x29000, v79
	s_nop 1
	s_mov_b64 exec, vcc
	global_store_short v74, v189, s[4:5]
	global_store_short v74, v190, s[4:5] offset:64
	global_store_short v74, v191, s[4:5] offset:128
	global_store_short v74, v192, s[4:5] offset:192
	s_mov_b64 exec, -1
	s_add_i32 s0, s0, s99
.Lpa_loop:
	s_cmp_lt_u32 s0, 0x29000
	s_cbranch_scc0 .Lpa_done
	s_add_i32 s45, s0, s99
	v_add_u32_e32 v43, s45, v129
	v_min_u32_e32 v145, 0x28fff, v43
	v_mul_hi_u32 v154, v145, s98
	v_add_u32_e32 v155, 0xfffd8000, v145
	v_lshrrev_b32_e32 v154, 3, v154
	v_lshrrev_b32_e32 v156, 1, v155
	v_and_b32_e32 v155, 1, v155
	v_mul_u32_u24_e32 v157, 10, v154
	v_add_u32_e32 v156, 0x4000, v156
	v_add_u32_e32 v155, 8, v155
	v_sub_u32_e32 v157, v145, v157
	v_cmp_gt_u32_e32 vcc, 0x28000, v145
	s_nop 1
	v_cndmask_b32_e32 v36, v156, v154, vcc
	v_cndmask_b32_e32 v37, v155, v157, vcc
	v_and_b32_e32 v146, 0x7ff, v36
	v_mul_u32_u24_e32 v147, 0x2600, v36
	v_lshl_add_u32 v147, v37, 8, v147
	v_add_u32_e32 v147, v147, v128
	global_load_ushort v39, v147, s[18:19]
	global_load_ushort v40, v147, s[18:19] offset:64
	global_load_ushort v41, v147, s[18:19] offset:128
	global_load_ushort v42, v147, s[18:19] offset:192
	v_lshrrev_b32_e32 v154, 6, v146
	v_and_b32_e32 v155, 63, v146
	v_lshl_add_u32 v154, v154, 8, v130
	v_lshl_add_u32 v155, v155, 8, v130
	ds_read_b64 v[32:33], v154
	ds_read_b64 v[34:35], v155
	v_lshrrev_b32_e32 v154, 11, v36
	v_add_u32_e32 v155, 0xffffc000, v36
	v_lshrrev_b32_e32 v155, 8, v155
	v_add_u32_e32 v156, 0x100, v146
	v_and_b32_e32 v157, 0xff, v36
	v_cmp_gt_u32_e32 vcc, 0x4000, v36
	v_lshl_add_u32 v38, v154, 3, v37
	v_lshlrev_b32_e32 v38, 19, v38
	v_cndmask_b32_e32 v155, v155, v154, vcc
	v_cndmask_b32_e32 v156, v157, v156, vcc
	v_lshl_add_u32 v38, v146, 8, v38
	v_lshl_add_u32 v155, v155, 1, v37
	v_add_u32_e32 v155, -8, v155
	v_mul_u32_u24_e32 v155, 0x900, v155
	v_add_u32_e32 v155, v155, v156
	v_lshlrev_b32_e32 v155, 8, v155
	v_add_u32_e32 v155, 0x2000000, v155
	v_cmp_gt_u32_e32 vcc, 8, v37
	s_nop 1
	v_cndmask_b32_e32 v38, v155, v38, vcc
	v_add_u32_e32 v38, v38, v128
	s_mul_i32 s44, s1, 1
	s_add_i32 s44, s44, s45
	v_add_u32_e32 v55, s44, v129
	v_min_u32_e32 v158, 0x28fff, v55
	v_mul_hi_u32 v167, v158, s98
	v_add_u32_e32 v168, 0xfffd8000, v158
	v_lshrrev_b32_e32 v167, 3, v167
	v_lshrrev_b32_e32 v169, 1, v168
	v_and_b32_e32 v168, 1, v168
	v_mul_u32_u24_e32 v170, 10, v167
	v_add_u32_e32 v169, 0x4000, v169
	v_add_u32_e32 v168, 8, v168
	v_sub_u32_e32 v170, v158, v170
	v_cmp_gt_u32_e32 vcc, 0x28000, v158
	s_nop 1
	v_cndmask_b32_e32 v48, v169, v167, vcc
	v_cndmask_b32_e32 v49, v168, v170, vcc
	v_and_b32_e32 v159, 0x7ff, v48
	v_mul_u32_u24_e32 v160, 0x2600, v48
	v_lshl_add_u32 v160, v49, 8, v160
	v_add_u32_e32 v160, v160, v128
	global_load_ushort v51, v160, s[18:19]
	global_load_ushort v52, v160, s[18:19] offset:64
	global_load_ushort v53, v160, s[18:19] offset:128
	global_load_ushort v54, v160, s[18:19] offset:192
	v_lshrrev_b32_e32 v167, 6, v159
	v_and_b32_e32 v168, 63, v159
	v_lshl_add_u32 v167, v167, 8, v130
	v_lshl_add_u32 v168, v168, 8, v130
	ds_read_b64 v[44:45], v167
	ds_read_b64 v[46:47], v168
	v_lshrrev_b32_e32 v167, 11, v48
	v_add_u32_e32 v168, 0xffffc000, v48
	v_lshrrev_b32_e32 v168, 8, v168
	v_add_u32_e32 v169, 0x100, v159
	v_and_b32_e32 v170, 0xff, v48
	v_cmp_gt_u32_e32 vcc, 0x4000, v48
	v_lshl_add_u32 v50, v167, 3, v49
	v_lshlrev_b32_e32 v50, 19, v50
	v_cndmask_b32_e32 v168, v168, v167, vcc
	v_cndmask_b32_e32 v169, v170, v169, vcc
	v_lshl_add_u32 v50, v159, 8, v50
	v_lshl_add_u32 v168, v168, 1, v49
	v_add_u32_e32 v168, -8, v168
	v_mul_u32_u24_e32 v168, 0x900, v168
	v_add_u32_e32 v168, v168, v169
	v_lshlrev_b32_e32 v168, 8, v168
	v_add_u32_e32 v168, 0x2000000, v168
	v_cmp_gt_u32_e32 vcc, 8, v49
	s_nop 1
	v_cndmask_b32_e32 v50, v168, v50, vcc
	v_add_u32_e32 v50, v50, v128
	s_mul_i32 s44, s1, 2
	s_add_i32 s44, s44, s45
	v_add_u32_e32 v67, s44, v129
	v_min_u32_e32 v171, 0x28fff, v67
	v_mul_hi_u32 v180, v171, s98
	v_add_u32_e32 v181, 0xfffd8000, v171
	v_lshrrev_b32_e32 v180, 3, v180
	v_lshrrev_b32_e32 v182, 1, v181
	v_and_b32_e32 v181, 1, v181
	v_mul_u32_u24_e32 v183, 10, v180
	v_add_u32_e32 v182, 0x4000, v182
	v_add_u32_e32 v181, 8, v181
	v_sub_u32_e32 v183, v171, v183
	v_cmp_gt_u32_e32 vcc, 0x28000, v171
	s_nop 1
	v_cndmask_b32_e32 v60, v182, v180, vcc
	v_cndmask_b32_e32 v61, v181, v183, vcc
	v_and_b32_e32 v172, 0x7ff, v60
	v_mul_u32_u24_e32 v173, 0x2600, v60
	v_lshl_add_u32 v173, v61, 8, v173
; __device__ __forceinline__ float bf2f(bf16_t h) { return __uint_as_float(((unsigned)h) << 16); }
; __device__ __forceinline__ void prep_phase(const Params& P, LAS unsigned char* lds) {
;     ...
;         for (int base = 0; base < NHR; base += 4 * nhw) {
;             float xv[4][4]; int rows[4], hhs[4];
; #pragma unroll
;             for (int u = 0; u < 4; ++u) {
;                 int idx = base + u * nhw + hw; if (idx >= NHR) idx = NHR - 1;
;                 int row, hh; if (idx < NTOK * 10) { row = idx / 10; hh = idx - row * 10; } else { const int j = idx - NTOK * 10; row = NTOK + (j >> 1); hh = 8 + (j & 1); }
;                 rows[u] = row; hhs[u] = hh;
;                 const int col0 = hh < 8 ? hh * 128 : C_AK + (hh - 8) * 128;
;                 const bf16_t* pr = proj + (size_t)row * INCP + col0 + i;
;                 xv[u][0] = bf2f(pr[0]); xv[u][1] = bf2f(pr[32]); xv[u][2] = bf2f(pr[64]); xv[u][3] = bf2f(pr[96]);
;             }
; #pragma unroll
;             for (int u = 0; u < 4; ++u) {
;                 const int row = rows[u], hh = hhs[u];
;                 float x0 = xv[u][0], x1 = xv[u][1], x2 = xv[u][2], x3 = xv[u][3];
;                 float ss = x0 * x0 + x1 * x1 + x2 * x2 + x3 * x3;
; #pragma unroll
;                 for (int o = 1; o < 32; o <<= 1) ss += __shfl_xor(ss, o);
;                 const float rstd = rsqrtf(ss * (1.f / 128.f) + 1e-6f);
	v_add_u32_e32 v173, v173, v128
	global_load_ushort v63, v173, s[18:19]
	global_load_ushort v64, v173, s[18:19] offset:64
	global_load_ushort v65, v173, s[18:19] offset:128
	global_load_ushort v66, v173, s[18:19] offset:192
	v_lshrrev_b32_e32 v180, 6, v172
	v_and_b32_e32 v181, 63, v172
	v_lshl_add_u32 v180, v180, 8, v130
	v_lshl_add_u32 v181, v181, 8, v130
	ds_read_b64 v[56:57], v180
	ds_read_b64 v[58:59], v181
	v_lshrrev_b32_e32 v180, 11, v60
	v_add_u32_e32 v181, 0xffffc000, v60
	v_lshrrev_b32_e32 v181, 8, v181
	v_add_u32_e32 v182, 0x100, v172
	v_and_b32_e32 v183, 0xff, v60
	v_cmp_gt_u32_e32 vcc, 0x4000, v60
	v_lshl_add_u32 v62, v180, 3, v61
	v_lshlrev_b32_e32 v62, 19, v62
	v_cndmask_b32_e32 v181, v181, v180, vcc
	v_cndmask_b32_e32 v182, v183, v182, vcc
	v_lshl_add_u32 v62, v172, 8, v62
	v_lshl_add_u32 v181, v181, 1, v61
	v_add_u32_e32 v181, -8, v181
	v_mul_u32_u24_e32 v181, 0x900, v181
	v_add_u32_e32 v181, v181, v182
	v_lshlrev_b32_e32 v181, 8, v181
	v_add_u32_e32 v181, 0x2000000, v181
	v_cmp_gt_u32_e32 vcc, 8, v61
	s_nop 1
	v_cndmask_b32_e32 v62, v181, v62, vcc
	v_add_u32_e32 v62, v62, v128
	s_mul_i32 s44, s1, 3
	s_add_i32 s44, s44, s45
	v_add_u32_e32 v79, s44, v129
	v_min_u32_e32 v184, 0x28fff, v79
	v_mul_hi_u32 v193, v184, s98
	v_add_u32_e32 v194, 0xfffd8000, v184
	v_lshrrev_b32_e32 v193, 3, v193
	v_lshrrev_b32_e32 v195, 1, v194
	v_and_b32_e32 v194, 1, v194
	v_mul_u32_u24_e32 v196, 10, v193
	v_add_u32_e32 v195, 0x4000, v195
	v_add_u32_e32 v194, 8, v194
	v_sub_u32_e32 v196, v184, v196
	v_cmp_gt_u32_e32 vcc, 0x28000, v184
	s_nop 1
	v_cndmask_b32_e32 v72, v195, v193, vcc
	v_cndmask_b32_e32 v73, v194, v196, vcc
	v_and_b32_e32 v185, 0x7ff, v72
	v_mul_u32_u24_e32 v186, 0x2600, v72
	v_lshl_add_u32 v186, v73, 8, v186
	v_add_u32_e32 v186, v186, v128
	global_load_ushort v75, v186, s[18:19]
	global_load_ushort v76, v186, s[18:19] offset:64
	global_load_ushort v77, v186, s[18:19] offset:128
	global_load_ushort v78, v186, s[18:19] offset:192
	v_lshrrev_b32_e32 v193, 6, v185
	v_and_b32_e32 v194, 63, v185
	v_lshl_add_u32 v193, v193, 8, v130
	v_lshl_add_u32 v194, v194, 8, v130
	ds_read_b64 v[68:69], v193
	ds_read_b64 v[70:71], v194
	v_lshrrev_b32_e32 v193, 11, v72
	v_add_u32_e32 v194, 0xffffc000, v72
	v_lshrrev_b32_e32 v194, 8, v194
	v_add_u32_e32 v195, 0x100, v185
	v_and_b32_e32 v196, 0xff, v72
	v_cmp_gt_u32_e32 vcc, 0x4000, v72
	v_lshl_add_u32 v74, v193, 3, v73
	v_lshlrev_b32_e32 v74, 19, v74
	v_cndmask_b32_e32 v194, v194, v193, vcc
	v_cndmask_b32_e32 v195, v196, v195, vcc
	v_lshl_add_u32 v74, v185, 8, v74
	v_lshl_add_u32 v194, v194, 1, v73
	v_add_u32_e32 v194, -8, v194
	v_mul_u32_u24_e32 v194, 0x900, v194
	v_add_u32_e32 v194, v194, v195
	v_lshlrev_b32_e32 v194, 8, v194
	v_add_u32_e32 v194, 0x2000000, v194
	v_cmp_gt_u32_e32 vcc, 8, v73
	s_nop 1
	v_cndmask_b32_e32 v74, v194, v74, vcc
	v_add_u32_e32 v74, v74, v128
	s_waitcnt vmcnt(32) lgkmcnt(0)
	v_lshlrev_b32_e32 v87, 16, v87
	v_lshlrev_b32_e32 v88, 16, v88
	v_lshlrev_b32_e32 v89, 16, v89
	v_lshlrev_b32_e32 v90, 16, v90
	v_mul_f32_e32 v154, v87, v87
	v_mul_f32_e32 v155, v88, v88
	v_mul_f32_e32 v156, v89, v89
	v_mul_f32_e32 v157, v90, v90
	v_add_f32_e32 v148, v154, v155
	v_add_f32_e32 v148, v156, v148
	v_add_f32_e32 v148, v157, v148
	v_lshlrev_b32_e32 v99, 16, v99
	v_lshlrev_b32_e32 v100, 16, v100
	v_lshlrev_b32_e32 v101, 16, v101
	v_lshlrev_b32_e32 v102, 16, v102
	v_mul_f32_e32 v167, v99, v99
	v_mul_f32_e32 v168, v100, v100
	v_mul_f32_e32 v169, v101, v101
	v_mul_f32_e32 v170, v102, v102
	v_add_f32_e32 v161, v167, v168
	v_add_f32_e32 v161, v169, v161
	v_add_f32_e32 v161, v170, v161
	v_lshlrev_b32_e32 v111, 16, v111
	v_lshlrev_b32_e32 v112, 16, v112
	v_lshlrev_b32_e32 v113, 16, v113
	v_lshlrev_b32_e32 v114, 16, v114
	v_mul_f32_e32 v180, v111, v111
	v_mul_f32_e32 v181, v112, v112
	v_mul_f32_e32 v182, v113, v113
	v_mul_f32_e32 v183, v114, v114
	v_add_f32_e32 v174, v180, v181
	v_add_f32_e32 v174, v182, v174
	v_add_f32_e32 v174, v183, v174
	v_lshlrev_b32_e32 v123, 16, v123
	v_lshlrev_b32_e32 v124, 16, v124
	v_lshlrev_b32_e32 v125, 16, v125
	v_lshlrev_b32_e32 v126, 16, v126
	v_mul_f32_e32 v193, v123, v123
	v_mul_f32_e32 v194, v124, v124
	v_mul_f32_e32 v195, v125, v125
	v_mul_f32_e32 v196, v126, v126
	v_add_f32_e32 v187, v193, v194
	v_add_f32_e32 v187, v195, v187
	v_add_f32_e32 v187, v196, v187
	s_nop 1
	v_add_f32_dpp v149, v148, v148 quad_perm:[1,0,3,2] row_mask:0xf bank_mask:0xf
	v_add_f32_dpp v162, v161, v161 quad_perm:[1,0,3,2] row_mask:0xf bank_mask:0xf
	v_add_f32_dpp v175, v174, v174 quad_perm:[1,0,3,2] row_mask:0xf bank_mask:0xf
	v_add_f32_dpp v188, v187, v187 quad_perm:[1,0,3,2] row_mask:0xf bank_mask:0xf
	v_mov_b32_e32 v148, v149
	v_mov_b32_e32 v161, v162
	v_mov_b32_e32 v174, v175
	v_mov_b32_e32 v187, v188
	s_nop 1
	v_add_f32_dpp v149, v148, v148 quad_perm:[2,3,0,1] row_mask:0xf bank_mask:0xf
	v_add_f32_dpp v162, v161, v161 quad_perm:[2,3,0,1] row_mask:0xf bank_mask:0xf
	v_add_f32_dpp v175, v174, v174 quad_perm:[2,3,0,1] row_mask:0xf bank_mask:0xf
	v_add_f32_dpp v188, v187, v187 quad_perm:[2,3,0,1] row_mask:0xf bank_mask:0xf
	v_mov_b32_e32 v148, v149
	v_mov_b32_e32 v161, v162
	v_mov_b32_e32 v174, v175
	v_mov_b32_e32 v187, v188
	s_nop 1
	v_add_f32_dpp v149, v148, v148 row_half_mirror row_mask:0xf bank_mask:0xf
	v_add_f32_dpp v162, v161, v161 row_half_mirror row_mask:0xf bank_mask:0xf
	v_add_f32_dpp v175, v174, v174 row_half_mirror row_mask:0xf bank_mask:0xf
	v_add_f32_dpp v188, v187, v187 row_half_mirror row_mask:0xf bank_mask:0xf
	v_mov_b32_e32 v148, v149
	v_mov_b32_e32 v161, v162
	v_mov_b32_e32 v174, v175
	v_mov_b32_e32 v187, v188
	s_nop 1
	v_add_f32_dpp v149, v148, v148 row_mirror row_mask:0xf bank_mask:0xf
	v_add_f32_dpp v162, v161, v161 row_mirror row_mask:0xf bank_mask:0xf
	v_add_f32_dpp v175, v174, v174 row_mirror row_mask:0xf bank_mask:0xf
	v_add_f32_dpp v188, v187, v187 row_mirror row_mask:0xf bank_mask:0xf
	v_mov_b32_e32 v148, v149
	v_mov_b32_e32 v161, v162
	v_mov_b32_e32 v174, v175
	v_mov_b32_e32 v187, v188
	ds_swizzle_b32 v149, v148 offset:swizzle(SWAP,16)
	ds_swizzle_b32 v162, v161 offset:swizzle(SWAP,16)
	ds_swizzle_b32 v175, v174 offset:swizzle(SWAP,16)
	ds_swizzle_b32 v188, v187 offset:swizzle(SWAP,16)
	s_waitcnt lgkmcnt(0)
; __device__ __forceinline__ bf16_t f2bf1(float x) { return (bf16_t)(cvt_pk_bf16(x, 0.f) & 0xffffu); }
; __device__ __forceinline__ void prep_phase(const Params& P, LAS unsigned char* lds) {
;     ...
;                 const int row = rows[u], hh = hhs[u];
;                 float x0 = xv[u][0], x1 = xv[u][1], x2 = xv[u][2], x3 = xv[u][3];
;                 float ss = x0 * x0 + x1 * x1 + x2 * x2 + x3 * x3;
; #pragma unroll
;                 for (int o = 1; o < 32; o <<= 1) ss += __shfl_xor(ss, o);
;                 const float rstd = rsqrtf(ss * (1.f / 128.f) + 1e-6f);
;                 if (hh < 8) { x0 *= rstd * gq0; x1 *= rstd * gq1; x2 *= rstd * gq2; x3 *= rstd * gq3; }
;                 else { x0 *= rstd * gk0; x1 *= rstd * gk1; x2 *= rstd * gk2; x3 *= rstd * gk3; }
;                 if (row < NTOK) {
;                     const int t = row & 2047, rr = t >> 6, cc = t & 63;
;                     float sr, cr, sc_, cc_; sincosf((float)rr * invf, &sr, &cr); sincosf((float)cc * invf, &sc_, &cc_);
;                     const float y0 = x0 * cr - x1 * sr, y1 = x1 * cr + x0 * sr, y2 = x2 * cc_ - x3 * sc_, y3 = x3 * cc_ + x2 * sc_;
;                     x0 = y0; x1 = y1; x2 = y2; x3 = y3;
;                 }
;                 bf16_t* op;
;                 if (hh < 8) { const int b = row >> 11, t = row & 2047; const float qs = QSCALE * LOG2E; x0 *= qs; x1 *= qs; x2 *= qs; x3 *= qs;
;                     op = Qp + ((size_t)(b * 8 + hh) * SEQ + t) * 128 + i; }
;                 else { int b, pos; if (row < NTOK) { b = row >> 11; pos = CTXL + (row & 2047); } else { b = (row - NTOK) >> 8; pos = (row - NTOK) & 255; }
;                     op = Kp + ((size_t)(b * 2 + (hh - 8)) * KVLEN + pos) * 128 + i; }
;                 if (base + u * nhw + hw < NHR) { op[0] = f2bf1(x0); op[32] = f2bf1(x1); op[64] = f2bf1(x2); op[96] = f2bf1(x3); }
	v_add_f32_e32 v148, v148, v149
	v_add_f32_e32 v161, v161, v162
	v_add_f32_e32 v174, v174, v175
	v_add_f32_e32 v187, v187, v188
	v_fmamk_f32 v148, v148, 0x3c000000, v140
	v_fmamk_f32 v161, v161, 0x3c000000, v140
	v_fmamk_f32 v174, v174, 0x3c000000, v140
	v_fmamk_f32 v187, v187, 0x3c000000, v140
	v_rsq_f32_e32 v148, v148
	v_rsq_f32_e32 v161, v161
	v_rsq_f32_e32 v174, v174
	v_rsq_f32_e32 v187, v187
	v_cmp_gt_u32_e32 vcc, 8, v85
	s_nop 1
	v_cndmask_b32_e32 v154, v136, v132, vcc
	v_cndmask_b32_e32 v155, v137, v133, vcc
	v_cndmask_b32_e32 v156, v138, v134, vcc
	v_cndmask_b32_e32 v157, v139, v135, vcc
	v_mul_f32_e32 v154, v154, v148
	v_mul_f32_e32 v155, v155, v148
	v_mul_f32_e32 v156, v156, v148
	v_mul_f32_e32 v157, v157, v148
	v_mul_f32_e32 v87, v154, v87
	v_mul_f32_e32 v88, v155, v88
	v_mul_f32_e32 v89, v156, v89
	v_mul_f32_e32 v90, v157, v90
	v_mul_f32_e32 v154, v88, v80
	v_mul_f32_e32 v155, v87, v80
	v_mul_f32_e32 v156, v90, v82
	v_mul_f32_e32 v157, v89, v82
	v_fma_f32 v150, v87, v81, -v154
	v_fma_f32 v151, v88, v81, v155
	v_fma_f32 v152, v89, v83, -v156
	v_fma_f32 v153, v90, v83, v157
	v_cmp_gt_u32_e32 vcc, 0x4000, v84
	s_nop 1
	v_cndmask_b32_e32 v150, v87, v150, vcc
	v_cndmask_b32_e32 v151, v88, v151, vcc
	v_cndmask_b32_e32 v152, v89, v152, vcc
	v_cndmask_b32_e32 v153, v90, v153, vcc
	v_mul_f32_e32 v154, 0x3e0293ee, v150
	v_mul_f32_e32 v155, 0x3e0293ee, v151
	v_mul_f32_e32 v156, 0x3e0293ee, v152
	v_mul_f32_e32 v157, 0x3e0293ee, v153
	v_cmp_gt_u32_e32 vcc, 8, v85
	s_nop 1
	v_cndmask_b32_e32 v150, v150, v154, vcc
	v_cndmask_b32_e32 v151, v151, v155, vcc
	v_cndmask_b32_e32 v152, v152, v156, vcc
	v_cndmask_b32_e32 v153, v153, v157, vcc
	v_cvt_pk_bf16_f32 v150, v150, v150
	v_cvt_pk_bf16_f32 v151, v151, v151
	v_cvt_pk_bf16_f32 v152, v152, v152
	v_cvt_pk_bf16_f32 v153, v153, v153
	v_cmp_gt_u32_e32 vcc, 0x29000, v91
	s_nop 1
	s_mov_b64 exec, vcc
	global_store_short v86, v150, s[4:5]
	global_store_short v86, v151, s[4:5] offset:64
	global_store_short v86, v152, s[4:5] offset:128
	global_store_short v86, v153, s[4:5] offset:192
	s_mov_b64 exec, -1
	v_cmp_gt_u32_e32 vcc, 8, v97
	s_nop 1
	v_cndmask_b32_e32 v167, v136, v132, vcc
	v_cndmask_b32_e32 v168, v137, v133, vcc
	v_cndmask_b32_e32 v169, v138, v134, vcc
	v_cndmask_b32_e32 v170, v139, v135, vcc
	v_mul_f32_e32 v167, v167, v161
	v_mul_f32_e32 v168, v168, v161
	v_mul_f32_e32 v169, v169, v161
	v_mul_f32_e32 v170, v170, v161
	v_mul_f32_e32 v99, v167, v99
	v_mul_f32_e32 v100, v168, v100
	v_mul_f32_e32 v101, v169, v101
	v_mul_f32_e32 v102, v170, v102
	v_mul_f32_e32 v167, v100, v92
	v_mul_f32_e32 v168, v99, v92
	v_mul_f32_e32 v169, v102, v94
	v_mul_f32_e32 v170, v101, v94
	v_fma_f32 v163, v99, v93, -v167
	v_fma_f32 v164, v100, v93, v168
	v_fma_f32 v165, v101, v95, -v169
	v_fma_f32 v166, v102, v95, v170
	v_cmp_gt_u32_e32 vcc, 0x4000, v96
	s_nop 1
	v_cndmask_b32_e32 v163, v99, v163, vcc
	v_cndmask_b32_e32 v164, v100, v164, vcc
	v_cndmask_b32_e32 v165, v101, v165, vcc
	v_cndmask_b32_e32 v166, v102, v166, vcc
	v_mul_f32_e32 v167, 0x3e0293ee, v163
	v_mul_f32_e32 v168, 0x3e0293ee, v164
	v_mul_f32_e32 v169, 0x3e0293ee, v165
	v_mul_f32_e32 v170, 0x3e0293ee, v166
	v_cmp_gt_u32_e32 vcc, 8, v97
	s_nop 1
	v_cndmask_b32_e32 v163, v163, v167, vcc
	v_cndmask_b32_e32 v164, v164, v168, vcc
	v_cndmask_b32_e32 v165, v165, v169, vcc
	v_cndmask_b32_e32 v166, v166, v170, vcc
	v_cvt_pk_bf16_f32 v163, v163, v163
	v_cvt_pk_bf16_f32 v164, v164, v164
	v_cvt_pk_bf16_f32 v165, v165, v165
	v_cvt_pk_bf16_f32 v166, v166, v166
	v_cmp_gt_u32_e32 vcc, 0x29000, v103
	s_nop 1
	s_mov_b64 exec, vcc
	global_store_short v98, v163, s[4:5]
	global_store_short v98, v164, s[4:5] offset:64
	global_store_short v98, v165, s[4:5] offset:128
	global_store_short v98, v166, s[4:5] offset:192
	s_mov_b64 exec, -1
	v_cmp_gt_u32_e32 vcc, 8, v109
	s_nop 1
	v_cndmask_b32_e32 v180, v136, v132, vcc
	v_cndmask_b32_e32 v181, v137, v133, vcc
	v_cndmask_b32_e32 v182, v138, v134, vcc
	v_cndmask_b32_e32 v183, v139, v135, vcc
	v_mul_f32_e32 v180, v180, v174
	v_mul_f32_e32 v181, v181, v174
	v_mul_f32_e32 v182, v182, v174
	v_mul_f32_e32 v183, v183, v174
	v_mul_f32_e32 v111, v180, v111
	v_mul_f32_e32 v112, v181, v112
	v_mul_f32_e32 v113, v182, v113
	v_mul_f32_e32 v114, v183, v114
	v_mul_f32_e32 v180, v112, v104
	v_mul_f32_e32 v181, v111, v104
	v_mul_f32_e32 v182, v114, v106
	v_mul_f32_e32 v183, v113, v106
	v_fma_f32 v176, v111, v105, -v180
	v_fma_f32 v177, v112, v105, v181
	v_fma_f32 v178, v113, v107, -v182
	v_fma_f32 v179, v114, v107, v183
	v_cmp_gt_u32_e32 vcc, 0x4000, v108
	s_nop 1
	v_cndmask_b32_e32 v176, v111, v176, vcc
	v_cndmask_b32_e32 v177, v112, v177, vcc
	v_cndmask_b32_e32 v178, v113, v178, vcc
	v_cndmask_b32_e32 v179, v114, v179, vcc
	v_mul_f32_e32 v180, 0x3e0293ee, v176
	v_mul_f32_e32 v181, 0x3e0293ee, v177
	v_mul_f32_e32 v182, 0x3e0293ee, v178
	v_mul_f32_e32 v183, 0x3e0293ee, v179
	v_cmp_gt_u32_e32 vcc, 8, v109
	s_nop 1
	v_cndmask_b32_e32 v176, v176, v180, vcc
	v_cndmask_b32_e32 v177, v177, v181, vcc
	v_cndmask_b32_e32 v178, v178, v182, vcc
	v_cndmask_b32_e32 v179, v179, v183, vcc
	v_cvt_pk_bf16_f32 v176, v176, v176
	v_cvt_pk_bf16_f32 v177, v177, v177
	v_cvt_pk_bf16_f32 v178, v178, v178
	v_cvt_pk_bf16_f32 v179, v179, v179
	v_cmp_gt_u32_e32 vcc, 0x29000, v115
	s_nop 1
	s_mov_b64 exec, vcc
	global_store_short v110, v176, s[4:5]
	global_store_short v110, v177, s[4:5] offset:64
	global_store_short v110, v178, s[4:5] offset:128
	global_store_short v110, v179, s[4:5] offset:192
	s_mov_b64 exec, -1
	v_cmp_gt_u32_e32 vcc, 8, v121
	s_nop 1
	v_cndmask_b32_e32 v193, v136, v132, vcc
	v_cndmask_b32_e32 v194, v137, v133, vcc
	v_cndmask_b32_e32 v195, v138, v134, vcc
; __device__ __forceinline__ float bf2f(bf16_t h) { return __uint_as_float(((unsigned)h) << 16); }
; __device__ __forceinline__ bf16_t f2bf1(float x) { return (bf16_t)(cvt_pk_bf16(x, 0.f) & 0xffffu); }
; __device__ __forceinline__ void prep_phase(const Params& P, LAS unsigned char* lds) {
;     ...
;         for (int base = 0; base < NHR; base += 4 * nhw) {
;             float xv[4][4]; int rows[4], hhs[4];
; #pragma unroll
;             for (int u = 0; u < 4; ++u) {
;                 int idx = base + u * nhw + hw; if (idx >= NHR) idx = NHR - 1;
;                 int row, hh; if (idx < NTOK * 10) { row = idx / 10; hh = idx - row * 10; } else { const int j = idx - NTOK * 10; row = NTOK + (j >> 1); hh = 8 + (j & 1); }
;                 rows[u] = row; hhs[u] = hh;
;                 const int col0 = hh < 8 ? hh * 128 : C_AK + (hh - 8) * 128;
;                 const bf16_t* pr = proj + (size_t)row * INCP + col0 + i;
;                 xv[u][0] = bf2f(pr[0]); xv[u][1] = bf2f(pr[32]); xv[u][2] = bf2f(pr[64]); xv[u][3] = bf2f(pr[96]);
;     ...
;                 bf16_t* op;
;                 if (hh < 8) { const int b = row >> 11, t = row & 2047; const float qs = QSCALE * LOG2E; x0 *= qs; x1 *= qs; x2 *= qs; x3 *= qs;
;                     op = Qp + ((size_t)(b * 8 + hh) * SEQ + t) * 128 + i; }
;                 else { int b, pos; if (row < NTOK) { b = row >> 11; pos = CTXL + (row & 2047); } else { b = (row - NTOK) >> 8; pos = (row - NTOK) & 255; }
;                     op = Kp + ((size_t)(b * 2 + (hh - 8)) * KVLEN + pos) * 128 + i; }
;                 if (base + u * nhw + hw < NHR) { op[0] = f2bf1(x0); op[32] = f2bf1(x1); op[64] = f2bf1(x2); op[96] = f2bf1(x3); }
	v_cndmask_b32_e32 v196, v139, v135, vcc
	v_mul_f32_e32 v193, v193, v187
	v_mul_f32_e32 v194, v194, v187
	v_mul_f32_e32 v195, v195, v187
	v_mul_f32_e32 v196, v196, v187
	v_mul_f32_e32 v123, v193, v123
	v_mul_f32_e32 v124, v194, v124
	v_mul_f32_e32 v125, v195, v125
	v_mul_f32_e32 v126, v196, v126
	v_mul_f32_e32 v193, v124, v116
	v_mul_f32_e32 v194, v123, v116
	v_mul_f32_e32 v195, v126, v118
	v_mul_f32_e32 v196, v125, v118
	v_fma_f32 v189, v123, v117, -v193
	v_fma_f32 v190, v124, v117, v194
	v_fma_f32 v191, v125, v119, -v195
	v_fma_f32 v192, v126, v119, v196
	v_cmp_gt_u32_e32 vcc, 0x4000, v120
	s_nop 1
	v_cndmask_b32_e32 v189, v123, v189, vcc
	v_cndmask_b32_e32 v190, v124, v190, vcc
	v_cndmask_b32_e32 v191, v125, v191, vcc
	v_cndmask_b32_e32 v192, v126, v192, vcc
	v_mul_f32_e32 v193, 0x3e0293ee, v189
	v_mul_f32_e32 v194, 0x3e0293ee, v190
	v_mul_f32_e32 v195, 0x3e0293ee, v191
	v_mul_f32_e32 v196, 0x3e0293ee, v192
	v_cmp_gt_u32_e32 vcc, 8, v121
	s_nop 1
	v_cndmask_b32_e32 v189, v189, v193, vcc
	v_cndmask_b32_e32 v190, v190, v194, vcc
	v_cndmask_b32_e32 v191, v191, v195, vcc
	v_cndmask_b32_e32 v192, v192, v196, vcc
	v_cvt_pk_bf16_f32 v189, v189, v189
	v_cvt_pk_bf16_f32 v190, v190, v190
	v_cvt_pk_bf16_f32 v191, v191, v191
	v_cvt_pk_bf16_f32 v192, v192, v192
	v_cmp_gt_u32_e32 vcc, 0x29000, v127
	s_nop 1
	s_mov_b64 exec, vcc
	global_store_short v122, v189, s[4:5]
	global_store_short v122, v190, s[4:5] offset:64
	global_store_short v122, v191, s[4:5] offset:128
	global_store_short v122, v192, s[4:5] offset:192
	s_mov_b64 exec, -1
	s_add_i32 s0, s0, s99
	s_cmp_lt_u32 s0, 0x29000
	s_cbranch_scc0 .Lpa_done
	s_add_i32 s45, s0, s99
	v_add_u32_e32 v91, s45, v129
	v_min_u32_e32 v145, 0x28fff, v91
	v_mul_hi_u32 v154, v145, s98
	v_add_u32_e32 v155, 0xfffd8000, v145
	v_lshrrev_b32_e32 v154, 3, v154
	v_lshrrev_b32_e32 v156, 1, v155
	v_and_b32_e32 v155, 1, v155
	v_mul_u32_u24_e32 v157, 10, v154
	v_add_u32_e32 v156, 0x4000, v156
	v_add_u32_e32 v155, 8, v155
	v_sub_u32_e32 v157, v145, v157
	v_cmp_gt_u32_e32 vcc, 0x28000, v145
	s_nop 1
	v_cndmask_b32_e32 v84, v156, v154, vcc
	v_cndmask_b32_e32 v85, v155, v157, vcc
	v_and_b32_e32 v146, 0x7ff, v84
	v_mul_u32_u24_e32 v147, 0x2600, v84
	v_lshl_add_u32 v147, v85, 8, v147
	v_add_u32_e32 v147, v147, v128
	global_load_ushort v87, v147, s[18:19]
	global_load_ushort v88, v147, s[18:19] offset:64
	global_load_ushort v89, v147, s[18:19] offset:128
	global_load_ushort v90, v147, s[18:19] offset:192
	v_lshrrev_b32_e32 v154, 6, v146
	v_and_b32_e32 v155, 63, v146
	v_lshl_add_u32 v154, v154, 8, v130
	v_lshl_add_u32 v155, v155, 8, v130
	ds_read_b64 v[80:81], v154
	ds_read_b64 v[82:83], v155
	v_lshrrev_b32_e32 v154, 11, v84
	v_add_u32_e32 v155, 0xffffc000, v84
	v_lshrrev_b32_e32 v155, 8, v155
	v_add_u32_e32 v156, 0x100, v146
	v_and_b32_e32 v157, 0xff, v84
	v_cmp_gt_u32_e32 vcc, 0x4000, v84
	v_lshl_add_u32 v86, v154, 3, v85
	v_lshlrev_b32_e32 v86, 19, v86
	v_cndmask_b32_e32 v155, v155, v154, vcc
	v_cndmask_b32_e32 v156, v157, v156, vcc
	v_lshl_add_u32 v86, v146, 8, v86
	v_lshl_add_u32 v155, v155, 1, v85
	v_add_u32_e32 v155, -8, v155
	v_mul_u32_u24_e32 v155, 0x900, v155
	v_add_u32_e32 v155, v155, v156
	v_lshlrev_b32_e32 v155, 8, v155
	v_add_u32_e32 v155, 0x2000000, v155
	v_cmp_gt_u32_e32 vcc, 8, v85
	s_nop 1
	v_cndmask_b32_e32 v86, v155, v86, vcc
	v_add_u32_e32 v86, v86, v128
	s_mul_i32 s44, s1, 1
	s_add_i32 s44, s44, s45
	v_add_u32_e32 v103, s44, v129
	v_min_u32_e32 v158, 0x28fff, v103
	v_mul_hi_u32 v167, v158, s98
	v_add_u32_e32 v168, 0xfffd8000, v158
	v_lshrrev_b32_e32 v167, 3, v167
	v_lshrrev_b32_e32 v169, 1, v168
	v_and_b32_e32 v168, 1, v168
	v_mul_u32_u24_e32 v170, 10, v167
	v_add_u32_e32 v169, 0x4000, v169
	v_add_u32_e32 v168, 8, v168
	v_sub_u32_e32 v170, v158, v170
	v_cmp_gt_u32_e32 vcc, 0x28000, v158
	s_nop 1
	v_cndmask_b32_e32 v96, v169, v167, vcc
	v_cndmask_b32_e32 v97, v168, v170, vcc
	v_and_b32_e32 v159, 0x7ff, v96
	v_mul_u32_u24_e32 v160, 0x2600, v96
	v_lshl_add_u32 v160, v97, 8, v160
	v_add_u32_e32 v160, v160, v128
	global_load_ushort v99, v160, s[18:19]
	global_load_ushort v100, v160, s[18:19] offset:64
	global_load_ushort v101, v160, s[18:19] offset:128
	global_load_ushort v102, v160, s[18:19] offset:192
	v_lshrrev_b32_e32 v167, 6, v159
	v_and_b32_e32 v168, 63, v159
	v_lshl_add_u32 v167, v167, 8, v130
	v_lshl_add_u32 v168, v168, 8, v130
	ds_read_b64 v[92:93], v167
	ds_read_b64 v[94:95], v168
	v_lshrrev_b32_e32 v167, 11, v96
	v_add_u32_e32 v168, 0xffffc000, v96
	v_lshrrev_b32_e32 v168, 8, v168
	v_add_u32_e32 v169, 0x100, v159
	v_and_b32_e32 v170, 0xff, v96
	v_cmp_gt_u32_e32 vcc, 0x4000, v96
	v_lshl_add_u32 v98, v167, 3, v97
	v_lshlrev_b32_e32 v98, 19, v98
	v_cndmask_b32_e32 v168, v168, v167, vcc
	v_cndmask_b32_e32 v169, v170, v169, vcc
	v_lshl_add_u32 v98, v159, 8, v98
	v_lshl_add_u32 v168, v168, 1, v97
	v_add_u32_e32 v168, -8, v168
	v_mul_u32_u24_e32 v168, 0x900, v168
	v_add_u32_e32 v168, v168, v169
	v_lshlrev_b32_e32 v168, 8, v168
	v_add_u32_e32 v168, 0x2000000, v168
	v_cmp_gt_u32_e32 vcc, 8, v97
	s_nop 1
	v_cndmask_b32_e32 v98, v168, v98, vcc
	v_add_u32_e32 v98, v98, v128
	s_mul_i32 s44, s1, 2
	s_add_i32 s44, s44, s45
	v_add_u32_e32 v115, s44, v129
	v_min_u32_e32 v171, 0x28fff, v115
	v_mul_hi_u32 v180, v171, s98
	v_add_u32_e32 v181, 0xfffd8000, v171
	v_lshrrev_b32_e32 v180, 3, v180
	v_lshrrev_b32_e32 v182, 1, v181
	v_and_b32_e32 v181, 1, v181
	v_mul_u32_u24_e32 v183, 10, v180
	v_add_u32_e32 v182, 0x4000, v182
	v_add_u32_e32 v181, 8, v181
	v_sub_u32_e32 v183, v171, v183
	v_cmp_gt_u32_e32 vcc, 0x28000, v171
	s_nop 1
	v_cndmask_b32_e32 v108, v182, v180, vcc
	v_cndmask_b32_e32 v109, v181, v183, vcc
; __device__ __forceinline__ float bf2f(bf16_t h) { return __uint_as_float(((unsigned)h) << 16); }
; __device__ __forceinline__ void prep_phase(const Params& P, LAS unsigned char* lds) {
;     ...
;             for (int u = 0; u < 4; ++u) {
;                 int idx = base + u * nhw + hw; if (idx >= NHR) idx = NHR - 1;
;                 int row, hh; if (idx < NTOK * 10) { row = idx / 10; hh = idx - row * 10; } else { const int j = idx - NTOK * 10; row = NTOK + (j >> 1); hh = 8 + (j & 1); }
;                 rows[u] = row; hhs[u] = hh;
;                 const int col0 = hh < 8 ? hh * 128 : C_AK + (hh - 8) * 128;
;                 const bf16_t* pr = proj + (size_t)row * INCP + col0 + i;
;                 xv[u][0] = bf2f(pr[0]); xv[u][1] = bf2f(pr[32]); xv[u][2] = bf2f(pr[64]); xv[u][3] = bf2f(pr[96]);
;             }
; #pragma unroll
;             for (int u = 0; u < 4; ++u) {
;                 const int row = rows[u], hh = hhs[u];
;                 float x0 = xv[u][0], x1 = xv[u][1], x2 = xv[u][2], x3 = xv[u][3];
;                 float ss = x0 * x0 + x1 * x1 + x2 * x2 + x3 * x3;
; #pragma unroll
;                 for (int o = 1; o < 32; o <<= 1) ss += __shfl_xor(ss, o);
	v_and_b32_e32 v172, 0x7ff, v108
	v_mul_u32_u24_e32 v173, 0x2600, v108
	v_lshl_add_u32 v173, v109, 8, v173
	v_add_u32_e32 v173, v173, v128
	global_load_ushort v111, v173, s[18:19]
	global_load_ushort v112, v173, s[18:19] offset:64
	global_load_ushort v113, v173, s[18:19] offset:128
	global_load_ushort v114, v173, s[18:19] offset:192
	v_lshrrev_b32_e32 v180, 6, v172
	v_and_b32_e32 v181, 63, v172
	v_lshl_add_u32 v180, v180, 8, v130
	v_lshl_add_u32 v181, v181, 8, v130
	ds_read_b64 v[104:105], v180
	ds_read_b64 v[106:107], v181
	v_lshrrev_b32_e32 v180, 11, v108
	v_add_u32_e32 v181, 0xffffc000, v108
	v_lshrrev_b32_e32 v181, 8, v181
	v_add_u32_e32 v182, 0x100, v172
	v_and_b32_e32 v183, 0xff, v108
	v_cmp_gt_u32_e32 vcc, 0x4000, v108
	v_lshl_add_u32 v110, v180, 3, v109
	v_lshlrev_b32_e32 v110, 19, v110
	v_cndmask_b32_e32 v181, v181, v180, vcc
	v_cndmask_b32_e32 v182, v183, v182, vcc
	v_lshl_add_u32 v110, v172, 8, v110
	v_lshl_add_u32 v181, v181, 1, v109
	v_add_u32_e32 v181, -8, v181
	v_mul_u32_u24_e32 v181, 0x900, v181
	v_add_u32_e32 v181, v181, v182
	v_lshlrev_b32_e32 v181, 8, v181
	v_add_u32_e32 v181, 0x2000000, v181
	v_cmp_gt_u32_e32 vcc, 8, v109
	s_nop 1
	v_cndmask_b32_e32 v110, v181, v110, vcc
	v_add_u32_e32 v110, v110, v128
	s_mul_i32 s44, s1, 3
	s_add_i32 s44, s44, s45
	v_add_u32_e32 v127, s44, v129
	v_min_u32_e32 v184, 0x28fff, v127
	v_mul_hi_u32 v193, v184, s98
	v_add_u32_e32 v194, 0xfffd8000, v184
	v_lshrrev_b32_e32 v193, 3, v193
	v_lshrrev_b32_e32 v195, 1, v194
	v_and_b32_e32 v194, 1, v194
	v_mul_u32_u24_e32 v196, 10, v193
	v_add_u32_e32 v195, 0x4000, v195
	v_add_u32_e32 v194, 8, v194
	v_sub_u32_e32 v196, v184, v196
	v_cmp_gt_u32_e32 vcc, 0x28000, v184
	s_nop 1
	v_cndmask_b32_e32 v120, v195, v193, vcc
	v_cndmask_b32_e32 v121, v194, v196, vcc
	v_and_b32_e32 v185, 0x7ff, v120
	v_mul_u32_u24_e32 v186, 0x2600, v120
	v_lshl_add_u32 v186, v121, 8, v186
	v_add_u32_e32 v186, v186, v128
	global_load_ushort v123, v186, s[18:19]
	global_load_ushort v124, v186, s[18:19] offset:64
	global_load_ushort v125, v186, s[18:19] offset:128
	global_load_ushort v126, v186, s[18:19] offset:192
	v_lshrrev_b32_e32 v193, 6, v185
	v_and_b32_e32 v194, 63, v185
	v_lshl_add_u32 v193, v193, 8, v130
	v_lshl_add_u32 v194, v194, 8, v130
	ds_read_b64 v[116:117], v193
	ds_read_b64 v[118:119], v194
	v_lshrrev_b32_e32 v193, 11, v120
	v_add_u32_e32 v194, 0xffffc000, v120
	v_lshrrev_b32_e32 v194, 8, v194
	v_add_u32_e32 v195, 0x100, v185
	v_and_b32_e32 v196, 0xff, v120
	v_cmp_gt_u32_e32 vcc, 0x4000, v120
	v_lshl_add_u32 v122, v193, 3, v121
	v_lshlrev_b32_e32 v122, 19, v122
	v_cndmask_b32_e32 v194, v194, v193, vcc
	v_cndmask_b32_e32 v195, v196, v195, vcc
	v_lshl_add_u32 v122, v185, 8, v122
	v_lshl_add_u32 v194, v194, 1, v121
	v_add_u32_e32 v194, -8, v194
	v_mul_u32_u24_e32 v194, 0x900, v194
	v_add_u32_e32 v194, v194, v195
	v_lshlrev_b32_e32 v194, 8, v194
	v_add_u32_e32 v194, 0x2000000, v194
	v_cmp_gt_u32_e32 vcc, 8, v121
	s_nop 1
	v_cndmask_b32_e32 v122, v194, v122, vcc
	v_add_u32_e32 v122, v122, v128
	s_waitcnt vmcnt(32) lgkmcnt(0)
	v_lshlrev_b32_e32 v39, 16, v39
	v_lshlrev_b32_e32 v40, 16, v40
	v_lshlrev_b32_e32 v41, 16, v41
	v_lshlrev_b32_e32 v42, 16, v42
	v_mul_f32_e32 v154, v39, v39
	v_mul_f32_e32 v155, v40, v40
	v_mul_f32_e32 v156, v41, v41
	v_mul_f32_e32 v157, v42, v42
	v_add_f32_e32 v148, v154, v155
	v_add_f32_e32 v148, v156, v148
	v_add_f32_e32 v148, v157, v148
	v_lshlrev_b32_e32 v51, 16, v51
	v_lshlrev_b32_e32 v52, 16, v52
	v_lshlrev_b32_e32 v53, 16, v53
	v_lshlrev_b32_e32 v54, 16, v54
	v_mul_f32_e32 v167, v51, v51
	v_mul_f32_e32 v168, v52, v52
	v_mul_f32_e32 v169, v53, v53
	v_mul_f32_e32 v170, v54, v54
	v_add_f32_e32 v161, v167, v168
	v_add_f32_e32 v161, v169, v161
	v_add_f32_e32 v161, v170, v161
	v_lshlrev_b32_e32 v63, 16, v63
	v_lshlrev_b32_e32 v64, 16, v64
	v_lshlrev_b32_e32 v65, 16, v65
	v_lshlrev_b32_e32 v66, 16, v66
	v_mul_f32_e32 v180, v63, v63
	v_mul_f32_e32 v181, v64, v64
	v_mul_f32_e32 v182, v65, v65
	v_mul_f32_e32 v183, v66, v66
	v_add_f32_e32 v174, v180, v181
	v_add_f32_e32 v174, v182, v174
	v_add_f32_e32 v174, v183, v174
	v_lshlrev_b32_e32 v75, 16, v75
	v_lshlrev_b32_e32 v76, 16, v76
	v_lshlrev_b32_e32 v77, 16, v77
	v_lshlrev_b32_e32 v78, 16, v78
	v_mul_f32_e32 v193, v75, v75
	v_mul_f32_e32 v194, v76, v76
	v_mul_f32_e32 v195, v77, v77
	v_mul_f32_e32 v196, v78, v78
	v_add_f32_e32 v187, v193, v194
	v_add_f32_e32 v187, v195, v187
	v_add_f32_e32 v187, v196, v187
	s_nop 1
	v_add_f32_dpp v149, v148, v148 quad_perm:[1,0,3,2] row_mask:0xf bank_mask:0xf
	v_add_f32_dpp v162, v161, v161 quad_perm:[1,0,3,2] row_mask:0xf bank_mask:0xf
	v_add_f32_dpp v175, v174, v174 quad_perm:[1,0,3,2] row_mask:0xf bank_mask:0xf
	v_add_f32_dpp v188, v187, v187 quad_perm:[1,0,3,2] row_mask:0xf bank_mask:0xf
	v_mov_b32_e32 v148, v149
	v_mov_b32_e32 v161, v162
	v_mov_b32_e32 v174, v175
	v_mov_b32_e32 v187, v188
	s_nop 1
	v_add_f32_dpp v149, v148, v148 quad_perm:[2,3,0,1] row_mask:0xf bank_mask:0xf
	v_add_f32_dpp v162, v161, v161 quad_perm:[2,3,0,1] row_mask:0xf bank_mask:0xf
	v_add_f32_dpp v175, v174, v174 quad_perm:[2,3,0,1] row_mask:0xf bank_mask:0xf
	v_add_f32_dpp v188, v187, v187 quad_perm:[2,3,0,1] row_mask:0xf bank_mask:0xf
	v_mov_b32_e32 v148, v149
	v_mov_b32_e32 v161, v162
	v_mov_b32_e32 v174, v175
	v_mov_b32_e32 v187, v188
	s_nop 1
	v_add_f32_dpp v149, v148, v148 row_half_mirror row_mask:0xf bank_mask:0xf
	v_add_f32_dpp v162, v161, v161 row_half_mirror row_mask:0xf bank_mask:0xf
	v_add_f32_dpp v175, v174, v174 row_half_mirror row_mask:0xf bank_mask:0xf
	v_add_f32_dpp v188, v187, v187 row_half_mirror row_mask:0xf bank_mask:0xf
	v_mov_b32_e32 v148, v149
	v_mov_b32_e32 v161, v162
	v_mov_b32_e32 v174, v175
	v_mov_b32_e32 v187, v188
	s_nop 1
	v_add_f32_dpp v149, v148, v148 row_mirror row_mask:0xf bank_mask:0xf
	v_add_f32_dpp v162, v161, v161 row_mirror row_mask:0xf bank_mask:0xf
	v_add_f32_dpp v175, v174, v174 row_mirror row_mask:0xf bank_mask:0xf
	v_add_f32_dpp v188, v187, v187 row_mirror row_mask:0xf bank_mask:0xf
	v_mov_b32_e32 v148, v149
	v_mov_b32_e32 v161, v162
	v_mov_b32_e32 v174, v175
	v_mov_b32_e32 v187, v188
	ds_swizzle_b32 v149, v148 offset:swizzle(SWAP,16)
	ds_swizzle_b32 v162, v161 offset:swizzle(SWAP,16)
	ds_swizzle_b32 v175, v174 offset:swizzle(SWAP,16)
	ds_swizzle_b32 v188, v187 offset:swizzle(SWAP,16)
	s_waitcnt lgkmcnt(0)
; __device__ __forceinline__ bf16_t f2bf1(float x) { return (bf16_t)(cvt_pk_bf16(x, 0.f) & 0xffffu); }
; __device__ __forceinline__ void prep_phase(const Params& P, LAS unsigned char* lds) {
;     ...
;                 float ss = x0 * x0 + x1 * x1 + x2 * x2 + x3 * x3;
; #pragma unroll
;                 for (int o = 1; o < 32; o <<= 1) ss += __shfl_xor(ss, o);
;                 const float rstd = rsqrtf(ss * (1.f / 128.f) + 1e-6f);
;                 if (hh < 8) { x0 *= rstd * gq0; x1 *= rstd * gq1; x2 *= rstd * gq2; x3 *= rstd * gq3; }
;                 else { x0 *= rstd * gk0; x1 *= rstd * gk1; x2 *= rstd * gk2; x3 *= rstd * gk3; }
;                 if (row < NTOK) {
;                     const int t = row & 2047, rr = t >> 6, cc = t & 63;
;                     float sr, cr, sc_, cc_; sincosf((float)rr * invf, &sr, &cr); sincosf((float)cc * invf, &sc_, &cc_);
;                     const float y0 = x0 * cr - x1 * sr, y1 = x1 * cr + x0 * sr, y2 = x2 * cc_ - x3 * sc_, y3 = x3 * cc_ + x2 * sc_;
;                     x0 = y0; x1 = y1; x2 = y2; x3 = y3;
;                 }
;                 bf16_t* op;
;                 if (hh < 8) { const int b = row >> 11, t = row & 2047; const float qs = QSCALE * LOG2E; x0 *= qs; x1 *= qs; x2 *= qs; x3 *= qs;
;                     op = Qp + ((size_t)(b * 8 + hh) * SEQ + t) * 128 + i; }
;                 else { int b, pos; if (row < NTOK) { b = row >> 11; pos = CTXL + (row & 2047); } else { b = (row - NTOK) >> 8; pos = (row - NTOK) & 255; }
;                     op = Kp + ((size_t)(b * 2 + (hh - 8)) * KVLEN + pos) * 128 + i; }
;                 if (base + u * nhw + hw < NHR) { op[0] = f2bf1(x0); op[32] = f2bf1(x1); op[64] = f2bf1(x2); op[96] = f2bf1(x3); }
	v_add_f32_e32 v148, v148, v149
	v_add_f32_e32 v161, v161, v162
	v_add_f32_e32 v174, v174, v175
	v_add_f32_e32 v187, v187, v188
	v_fmamk_f32 v148, v148, 0x3c000000, v140
	v_fmamk_f32 v161, v161, 0x3c000000, v140
	v_fmamk_f32 v174, v174, 0x3c000000, v140
	v_fmamk_f32 v187, v187, 0x3c000000, v140
	v_rsq_f32_e32 v148, v148
	v_rsq_f32_e32 v161, v161
	v_rsq_f32_e32 v174, v174
	v_rsq_f32_e32 v187, v187
	v_cmp_gt_u32_e32 vcc, 8, v37
	s_nop 1
	v_cndmask_b32_e32 v154, v136, v132, vcc
	v_cndmask_b32_e32 v155, v137, v133, vcc
	v_cndmask_b32_e32 v156, v138, v134, vcc
	v_cndmask_b32_e32 v157, v139, v135, vcc
	v_mul_f32_e32 v154, v154, v148
	v_mul_f32_e32 v155, v155, v148
	v_mul_f32_e32 v156, v156, v148
	v_mul_f32_e32 v157, v157, v148
	v_mul_f32_e32 v39, v154, v39
	v_mul_f32_e32 v40, v155, v40
	v_mul_f32_e32 v41, v156, v41
	v_mul_f32_e32 v42, v157, v42
	v_mul_f32_e32 v154, v40, v32
	v_mul_f32_e32 v155, v39, v32
	v_mul_f32_e32 v156, v42, v34
	v_mul_f32_e32 v157, v41, v34
	v_fma_f32 v150, v39, v33, -v154
	v_fma_f32 v151, v40, v33, v155
	v_fma_f32 v152, v41, v35, -v156
	v_fma_f32 v153, v42, v35, v157
	v_cmp_gt_u32_e32 vcc, 0x4000, v36
	s_nop 1
	v_cndmask_b32_e32 v150, v39, v150, vcc
	v_cndmask_b32_e32 v151, v40, v151, vcc
	v_cndmask_b32_e32 v152, v41, v152, vcc
	v_cndmask_b32_e32 v153, v42, v153, vcc
	v_mul_f32_e32 v154, 0x3e0293ee, v150
	v_mul_f32_e32 v155, 0x3e0293ee, v151
	v_mul_f32_e32 v156, 0x3e0293ee, v152
	v_mul_f32_e32 v157, 0x3e0293ee, v153
	v_cmp_gt_u32_e32 vcc, 8, v37
	s_nop 1
	v_cndmask_b32_e32 v150, v150, v154, vcc
	v_cndmask_b32_e32 v151, v151, v155, vcc
	v_cndmask_b32_e32 v152, v152, v156, vcc
	v_cndmask_b32_e32 v153, v153, v157, vcc
	v_cvt_pk_bf16_f32 v150, v150, v150
	v_cvt_pk_bf16_f32 v151, v151, v151
	v_cvt_pk_bf16_f32 v152, v152, v152
	v_cvt_pk_bf16_f32 v153, v153, v153
	v_cmp_gt_u32_e32 vcc, 0x29000, v43
	s_nop 1
	s_mov_b64 exec, vcc
	global_store_short v38, v150, s[4:5]
	global_store_short v38, v151, s[4:5] offset:64
	global_store_short v38, v152, s[4:5] offset:128
	global_store_short v38, v153, s[4:5] offset:192
	s_mov_b64 exec, -1
	v_cmp_gt_u32_e32 vcc, 8, v49
	s_nop 1
	v_cndmask_b32_e32 v167, v136, v132, vcc
	v_cndmask_b32_e32 v168, v137, v133, vcc
	v_cndmask_b32_e32 v169, v138, v134, vcc
	v_cndmask_b32_e32 v170, v139, v135, vcc
	v_mul_f32_e32 v167, v167, v161
	v_mul_f32_e32 v168, v168, v161
	v_mul_f32_e32 v169, v169, v161
	v_mul_f32_e32 v170, v170, v161
	v_mul_f32_e32 v51, v167, v51
	v_mul_f32_e32 v52, v168, v52
	v_mul_f32_e32 v53, v169, v53
	v_mul_f32_e32 v54, v170, v54
	v_mul_f32_e32 v167, v52, v44
	v_mul_f32_e32 v168, v51, v44
	v_mul_f32_e32 v169, v54, v46
	v_mul_f32_e32 v170, v53, v46
	v_fma_f32 v163, v51, v45, -v167
	v_fma_f32 v164, v52, v45, v168
	v_fma_f32 v165, v53, v47, -v169
	v_fma_f32 v166, v54, v47, v170
	v_cmp_gt_u32_e32 vcc, 0x4000, v48
	s_nop 1
	v_cndmask_b32_e32 v163, v51, v163, vcc
	v_cndmask_b32_e32 v164, v52, v164, vcc
	v_cndmask_b32_e32 v165, v53, v165, vcc
	v_cndmask_b32_e32 v166, v54, v166, vcc
	v_mul_f32_e32 v167, 0x3e0293ee, v163
	v_mul_f32_e32 v168, 0x3e0293ee, v164
	v_mul_f32_e32 v169, 0x3e0293ee, v165
	v_mul_f32_e32 v170, 0x3e0293ee, v166
	v_cmp_gt_u32_e32 vcc, 8, v49
	s_nop 1
	v_cndmask_b32_e32 v163, v163, v167, vcc
	v_cndmask_b32_e32 v164, v164, v168, vcc
	v_cndmask_b32_e32 v165, v165, v169, vcc
	v_cndmask_b32_e32 v166, v166, v170, vcc
	v_cvt_pk_bf16_f32 v163, v163, v163
	v_cvt_pk_bf16_f32 v164, v164, v164
	v_cvt_pk_bf16_f32 v165, v165, v165
	v_cvt_pk_bf16_f32 v166, v166, v166
	v_cmp_gt_u32_e32 vcc, 0x29000, v55
	s_nop 1
	s_mov_b64 exec, vcc
	global_store_short v50, v163, s[4:5]
; __device__ __forceinline__ bf16_t f2bf1(float x) { return (bf16_t)(cvt_pk_bf16(x, 0.f) & 0xffffu); }
; __device__ __forceinline__ void prep_phase(const Params& P, LAS unsigned char* lds) {
;     ...
;                 if (hh < 8) { x0 *= rstd * gq0; x1 *= rstd * gq1; x2 *= rstd * gq2; x3 *= rstd * gq3; }
;                 else { x0 *= rstd * gk0; x1 *= rstd * gk1; x2 *= rstd * gk2; x3 *= rstd * gk3; }
;                 if (row < NTOK) {
;                     const int t = row & 2047, rr = t >> 6, cc = t & 63;
;                     float sr, cr, sc_, cc_; sincosf((float)rr * invf, &sr, &cr); sincosf((float)cc * invf, &sc_, &cc_);
;                     const float y0 = x0 * cr - x1 * sr, y1 = x1 * cr + x0 * sr, y2 = x2 * cc_ - x3 * sc_, y3 = x3 * cc_ + x2 * sc_;
;                     x0 = y0; x1 = y1; x2 = y2; x3 = y3;
;                 }
;                 bf16_t* op;
;                 if (hh < 8) { const int b = row >> 11, t = row & 2047; const float qs = QSCALE * LOG2E; x0 *= qs; x1 *= qs; x2 *= qs; x3 *= qs;
;                     op = Qp + ((size_t)(b * 8 + hh) * SEQ + t) * 128 + i; }
;                 else { int b, pos; if (row < NTOK) { b = row >> 11; pos = CTXL + (row & 2047); } else { b = (row - NTOK) >> 8; pos = (row - NTOK) & 255; }
;                     op = Kp + ((size_t)(b * 2 + (hh - 8)) * KVLEN + pos) * 128 + i; }
;                 if (base + u * nhw + hw < NHR) { op[0] = f2bf1(x0); op[32] = f2bf1(x1); op[64] = f2bf1(x2); op[96] = f2bf1(x3); }
;             }
;         }
	global_store_short v50, v164, s[4:5] offset:64
	global_store_short v50, v165, s[4:5] offset:128
	global_store_short v50, v166, s[4:5] offset:192
	s_mov_b64 exec, -1
	v_cmp_gt_u32_e32 vcc, 8, v61
	s_nop 1
	v_cndmask_b32_e32 v180, v136, v132, vcc
	v_cndmask_b32_e32 v181, v137, v133, vcc
	v_cndmask_b32_e32 v182, v138, v134, vcc
	v_cndmask_b32_e32 v183, v139, v135, vcc
	v_mul_f32_e32 v180, v180, v174
	v_mul_f32_e32 v181, v181, v174
	v_mul_f32_e32 v182, v182, v174
	v_mul_f32_e32 v183, v183, v174
	v_mul_f32_e32 v63, v180, v63
	v_mul_f32_e32 v64, v181, v64
	v_mul_f32_e32 v65, v182, v65
	v_mul_f32_e32 v66, v183, v66
	v_mul_f32_e32 v180, v64, v56
	v_mul_f32_e32 v181, v63, v56
	v_mul_f32_e32 v182, v66, v58
	v_mul_f32_e32 v183, v65, v58
	v_fma_f32 v176, v63, v57, -v180
	v_fma_f32 v177, v64, v57, v181
	v_fma_f32 v178, v65, v59, -v182
	v_fma_f32 v179, v66, v59, v183
	v_cmp_gt_u32_e32 vcc, 0x4000, v60
	s_nop 1
	v_cndmask_b32_e32 v176, v63, v176, vcc
	v_cndmask_b32_e32 v177, v64, v177, vcc
	v_cndmask_b32_e32 v178, v65, v178, vcc
	v_cndmask_b32_e32 v179, v66, v179, vcc
	v_mul_f32_e32 v180, 0x3e0293ee, v176
	v_mul_f32_e32 v181, 0x3e0293ee, v177
	v_mul_f32_e32 v182, 0x3e0293ee, v178
	v_mul_f32_e32 v183, 0x3e0293ee, v179
	v_cmp_gt_u32_e32 vcc, 8, v61
	s_nop 1
	v_cndmask_b32_e32 v176, v176, v180, vcc
	v_cndmask_b32_e32 v177, v177, v181, vcc
	v_cndmask_b32_e32 v178, v178, v182, vcc
	v_cndmask_b32_e32 v179, v179, v183, vcc
	v_cvt_pk_bf16_f32 v176, v176, v176
	v_cvt_pk_bf16_f32 v177, v177, v177
	v_cvt_pk_bf16_f32 v178, v178, v178
	v_cvt_pk_bf16_f32 v179, v179, v179
	v_cmp_gt_u32_e32 vcc, 0x29000, v67
	s_nop 1
	s_mov_b64 exec, vcc
	global_store_short v62, v176, s[4:5]
	global_store_short v62, v177, s[4:5] offset:64
	global_store_short v62, v178, s[4:5] offset:128
	global_store_short v62, v179, s[4:5] offset:192
	s_mov_b64 exec, -1
	v_cmp_gt_u32_e32 vcc, 8, v73
	s_nop 1
	v_cndmask_b32_e32 v193, v136, v132, vcc
	v_cndmask_b32_e32 v194, v137, v133, vcc
	v_cndmask_b32_e32 v195, v138, v134, vcc
	v_cndmask_b32_e32 v196, v139, v135, vcc
	v_mul_f32_e32 v193, v193, v187
	v_mul_f32_e32 v194, v194, v187
	v_mul_f32_e32 v195, v195, v187
	v_mul_f32_e32 v196, v196, v187
	v_mul_f32_e32 v75, v193, v75
	v_mul_f32_e32 v76, v194, v76
	v_mul_f32_e32 v77, v195, v77
	v_mul_f32_e32 v78, v196, v78
	v_mul_f32_e32 v193, v76, v68
	v_mul_f32_e32 v194, v75, v68
	v_mul_f32_e32 v195, v78, v70
	v_mul_f32_e32 v196, v77, v70
	v_fma_f32 v189, v75, v69, -v193
	v_fma_f32 v190, v76, v69, v194
	v_fma_f32 v191, v77, v71, -v195
	v_fma_f32 v192, v78, v71, v196
	v_cmp_gt_u32_e32 vcc, 0x4000, v72
	s_nop 1
	v_cndmask_b32_e32 v189, v75, v189, vcc
	v_cndmask_b32_e32 v190, v76, v190, vcc
	v_cndmask_b32_e32 v191, v77, v191, vcc
	v_cndmask_b32_e32 v192, v78, v192, vcc
	v_mul_f32_e32 v193, 0x3e0293ee, v189
	v_mul_f32_e32 v194, 0x3e0293ee, v190
	v_mul_f32_e32 v195, 0x3e0293ee, v191
	v_mul_f32_e32 v196, 0x3e0293ee, v192
	v_cmp_gt_u32_e32 vcc, 8, v73
	s_nop 1
	v_cndmask_b32_e32 v189, v189, v193, vcc
	v_cndmask_b32_e32 v190, v190, v194, vcc
	v_cndmask_b32_e32 v191, v191, v195, vcc
	v_cndmask_b32_e32 v192, v192, v196, vcc
	v_cvt_pk_bf16_f32 v189, v189, v189
	v_cvt_pk_bf16_f32 v190, v190, v190
	v_cvt_pk_bf16_f32 v191, v191, v191
	v_cvt_pk_bf16_f32 v192, v192, v192
	v_cmp_gt_u32_e32 vcc, 0x29000, v79
	s_nop 1
	s_mov_b64 exec, vcc
	global_store_short v74, v189, s[4:5]
	global_store_short v74, v190, s[4:5] offset:64
	global_store_short v74, v191, s[4:5] offset:128
	global_store_short v74, v192, s[4:5] offset:192
	s_mov_b64 exec, -1
	s_add_i32 s0, s0, s99
	s_branch .Lpa_loop
.Lpa_done:
	s_waitcnt lgkmcnt(0)
	s_barrier
